# v117 + K-loop back-edge: counter/exit-test SALU moved ahead of the loop-back barrier (7.11 partial rotation)
# baseline (speedup 1.0000x reference)
.LBB0_132:
	s_add_u32 s36, s34, 0xfff00080
	s_addc_u32 s37, s35, -1
	s_add_i32 s68, 0, 0x10000
	s_cmp_eq_u32 s67, 60
	s_cselect_b32 s41, s25, s37
	s_cselect_b32 s40, s61, s36
	v_add_u32_e32 v144, s68, v147
	s_cselect_b32 s37, s23, s66
	s_cselect_b32 s36, s62, s63
	s_add_i32 s70, 0, 0x14000
	s_waitcnt lgkmcnt(0)
	ds_read_b128 v[152:155], v144
	ds_read_b128 v[156:159], v144 offset:1024
	ds_read_b128 v[160:163], v144 offset:2048
	ds_read_b128 v[164:167], v144 offset:3072
	v_add_u32_e32 v144, s70, v147
	ds_read_b128 v[168:171], v144
	ds_read_b128 v[172:175], v144 offset:1024
	ds_read_b128 v[176:179], v144 offset:2048
	ds_read_b128 v[180:183], v144 offset:3072
	v_lshl_add_u64 v[212:213], s[34:35], 0, v[140:141]
	s_add_i32 m0, s51, 0xc000
	ds_read_b128 v[184:187], v151
	ds_read_b128 v[188:191], v151 offset:1024
	ds_read_b128 v[192:195], v151 offset:2048
	ds_read_b128 v[196:199], v151 offset:3072
	ds_read_b128 v[200:203], v151 offset:4096
	ds_read_b128 v[204:207], v151 offset:5120
	ds_read_b128 v[208:211], v151 offset:6144
	ds_read_b128 v[216:219], v151 offset:7168
	global_load_lds_dwordx4 v[212:213], off
	v_lshl_add_u64 v[212:213], s[34:35], 0, v[142:143]
	s_add_i32 m0, s51, 0xe000
	s_nop 0
	global_load_lds_dwordx4 v[212:213], off
	s_waitcnt vmcnt(8)
	s_waitcnt lgkmcnt(0)
	s_barrier
	s_waitcnt lgkmcnt(0)
	v_mfma_f32_16x16x32_bf16 v[82:85], v[152:155], v[184:187], v[82:85]
	v_mfma_f32_16x16x32_bf16 v[74:77], v[160:163], v[184:187], v[74:77]
	v_mfma_f32_16x16x32_bf16 v[70:73], v[152:155], v[192:195], v[70:73]
	v_mfma_f32_16x16x32_bf16 v[62:65], v[160:163], v[192:195], v[62:65]
	v_mfma_f32_16x16x32_bf16 v[54:57], v[152:155], v[200:203], v[54:57]
	v_mfma_f32_16x16x32_bf16 v[50:53], v[160:163], v[200:203], v[50:53]
	v_mfma_f32_16x16x32_bf16 v[38:41], v[152:155], v[208:211], v[38:41]
	v_mfma_f32_16x16x32_bf16 v[34:37], v[160:163], v[208:211], v[34:37]
	v_mfma_f32_16x16x32_bf16 v[82:85], v[156:159], v[188:191], v[82:85]
	v_mfma_f32_16x16x32_bf16 v[74:77], v[164:167], v[188:191], v[74:77]
	v_mfma_f32_16x16x32_bf16 v[70:73], v[156:159], v[196:199], v[70:73]
	v_mfma_f32_16x16x32_bf16 v[62:65], v[164:167], v[196:199], v[62:65]
	v_mfma_f32_16x16x32_bf16 v[54:57], v[156:159], v[204:207], v[54:57]
	v_mfma_f32_16x16x32_bf16 v[50:53], v[164:167], v[204:207], v[50:53]
	v_mfma_f32_16x16x32_bf16 v[38:41], v[156:159], v[216:219], v[38:41]
	v_mfma_f32_16x16x32_bf16 v[34:37], v[164:167], v[216:219], v[34:37]
	v_mfma_f32_16x16x32_bf16 v[126:129], v[168:171], v[184:187], v[126:129]
	v_mfma_f32_16x16x32_bf16 v[122:125], v[176:179], v[184:187], v[122:125]
	v_mfma_f32_16x16x32_bf16 v[118:121], v[168:171], v[192:195], v[118:121]
	v_mfma_f32_16x16x32_bf16 v[114:117], v[176:179], v[192:195], v[114:117]
	v_mfma_f32_16x16x32_bf16 v[110:113], v[168:171], v[200:203], v[110:113]
	v_mfma_f32_16x16x32_bf16 v[106:109], v[176:179], v[200:203], v[106:109]
	v_mfma_f32_16x16x32_bf16 v[102:105], v[168:171], v[208:211], v[102:105]
	v_mfma_f32_16x16x32_bf16 v[98:101], v[176:179], v[208:211], v[98:101]
	v_mfma_f32_16x16x32_bf16 v[126:129], v[172:175], v[188:191], v[126:129]
	v_mfma_f32_16x16x32_bf16 v[122:125], v[180:183], v[188:191], v[122:125]
	v_mfma_f32_16x16x32_bf16 v[118:121], v[172:175], v[196:199], v[118:121]
	v_mfma_f32_16x16x32_bf16 v[114:117], v[180:183], v[196:199], v[114:117]
	v_mfma_f32_16x16x32_bf16 v[110:113], v[172:175], v[204:207], v[110:113]
	v_mfma_f32_16x16x32_bf16 v[106:109], v[180:183], v[204:207], v[106:109]
	v_mfma_f32_16x16x32_bf16 v[102:105], v[172:175], v[216:219], v[102:105]
	v_mfma_f32_16x16x32_bf16 v[98:101], v[180:183], v[216:219], v[98:101]
	s_barrier
	s_add_i32 s68, s68, s50
	v_lshl_add_u64 v[212:213], s[36:37], 0, v[130:131]
	s_mov_b32 m0, s68
	ds_read_b128 v[184:187], v151 offset:16384
	ds_read_b128 v[188:191], v151 offset:17408
	ds_read_b128 v[192:195], v151 offset:18432
	ds_read_b128 v[196:199], v151 offset:19456
	ds_read_b128 v[200:203], v151 offset:20480
	ds_read_b128 v[204:207], v151 offset:21504
	ds_read_b128 v[208:211], v151 offset:22528
	ds_read_b128 v[216:219], v151 offset:23552
	global_load_lds_dwordx4 v[212:213], off
	s_add_i32 m0, s68, 0x2000
	s_add_u32 s68, s36, 0x100000
	v_lshl_add_u64 v[220:221], s[36:37], 0, v[132:133]
	s_addc_u32 s69, s37, 0
	s_add_i32 s70, s70, s50
	global_load_lds_dwordx4 v[220:221], off
	v_lshl_add_u64 v[222:223], s[68:69], 0, v[130:131]
	s_mov_b32 m0, s70
	v_lshl_add_u64 v[224:225], s[40:41], 0, v[134:135]
	global_load_lds_dwordx4 v[222:223], off
	v_lshl_add_u64 v[222:223], s[68:69], 0, v[132:133]
	s_add_i32 m0, s70, 0x2000
	s_nop 0
	global_load_lds_dwordx4 v[222:223], off
	v_lshl_add_u64 v[222:223], s[40:41], 0, v[136:137]
	s_mov_b32 m0, s51
	s_nop 0
	global_load_lds_dwordx4 v[222:223], off
	s_mov_b32 m0, s52
	s_nop 0
	global_load_lds_dwordx4 v[224:225], off
	s_waitcnt vmcnt(8)
	s_waitcnt lgkmcnt(0)
	s_barrier
	s_waitcnt lgkmcnt(0)
	v_mfma_f32_16x16x32_bf16 v[30:33], v[152:155], v[184:187], v[30:33]
	v_mfma_f32_16x16x32_bf16 v[26:29], v[160:163], v[184:187], v[26:29]
	v_mfma_f32_16x16x32_bf16 v[22:25], v[152:155], v[192:195], v[22:25]
	v_mfma_f32_16x16x32_bf16 v[18:21], v[160:163], v[192:195], v[18:21]
	v_mfma_f32_16x16x32_bf16 v[14:17], v[152:155], v[200:203], v[14:17]
	v_mfma_f32_16x16x32_bf16 v[10:13], v[160:163], v[200:203], v[10:13]
	v_mfma_f32_16x16x32_bf16 v[6:9], v[152:155], v[208:211], v[6:9]
	v_mfma_f32_16x16x32_bf16 v[2:5], v[160:163], v[208:211], v[2:5]
	v_mfma_f32_16x16x32_bf16 v[30:33], v[156:159], v[188:191], v[30:33]
	v_mfma_f32_16x16x32_bf16 v[26:29], v[164:167], v[188:191], v[26:29]
	v_mfma_f32_16x16x32_bf16 v[22:25], v[156:159], v[196:199], v[22:25]
	v_mfma_f32_16x16x32_bf16 v[18:21], v[164:167], v[196:199], v[18:21]
	v_mfma_f32_16x16x32_bf16 v[14:17], v[156:159], v[204:207], v[14:17]
	v_mfma_f32_16x16x32_bf16 v[10:13], v[164:167], v[204:207], v[10:13]
	v_mfma_f32_16x16x32_bf16 v[6:9], v[156:159], v[216:219], v[6:9]
	v_mfma_f32_16x16x32_bf16 v[2:5], v[164:167], v[216:219], v[2:5]
	v_mfma_f32_16x16x32_bf16 v[94:97], v[168:171], v[184:187], v[94:97]
	v_mfma_f32_16x16x32_bf16 v[90:93], v[176:179], v[184:187], v[90:93]
	v_mfma_f32_16x16x32_bf16 v[86:89], v[168:171], v[192:195], v[86:89]
	v_mfma_f32_16x16x32_bf16 v[78:81], v[176:179], v[192:195], v[78:81]
	v_mfma_f32_16x16x32_bf16 v[66:69], v[168:171], v[200:203], v[66:69]
	v_mfma_f32_16x16x32_bf16 v[58:61], v[176:179], v[200:203], v[58:61]
	v_mfma_f32_16x16x32_bf16 v[46:49], v[168:171], v[208:211], v[46:49]
	v_mfma_f32_16x16x32_bf16 v[42:45], v[176:179], v[208:211], v[42:45]
	v_mfma_f32_16x16x32_bf16 v[94:97], v[172:175], v[188:191], v[94:97]
	v_mfma_f32_16x16x32_bf16 v[90:93], v[180:183], v[188:191], v[90:93]
	v_mfma_f32_16x16x32_bf16 v[86:89], v[172:175], v[196:199], v[86:89]
	v_mfma_f32_16x16x32_bf16 v[78:81], v[180:183], v[196:199], v[78:81]
	v_mfma_f32_16x16x32_bf16 v[66:69], v[172:175], v[204:207], v[66:69]
	v_mfma_f32_16x16x32_bf16 v[58:61], v[180:183], v[204:207], v[58:61]
	v_mfma_f32_16x16x32_bf16 v[46:49], v[172:175], v[216:219], v[46:49]
	v_mfma_f32_16x16x32_bf16 v[42:45], v[180:183], v[216:219], v[42:45]
	s_barrier
	s_add_i32 s68, 0, 0x18000
	v_add_u32_e32 v144, s68, v147
	s_add_i32 s69, 0, 0x1c000
	ds_read_b128 v[152:155], v144
	ds_read_b128 v[156:159], v144 offset:1024
	ds_read_b128 v[160:163], v144 offset:2048
	ds_read_b128 v[164:167], v144 offset:3072
	v_add_u32_e32 v144, s69, v147
	ds_read_b128 v[168:171], v144
	ds_read_b128 v[172:175], v144 offset:1024
	ds_read_b128 v[176:179], v144 offset:2048
	ds_read_b128 v[180:183], v144 offset:3072
	s_add_u32 s40, s40, 0x100000
	s_addc_u32 s41, s41, 0
	s_mov_b32 m0, s53
	v_lshl_add_u64 v[226:227], s[40:41], 0, v[136:137]
	ds_read_b128 v[184:187], v151 offset:32768
	ds_read_b128 v[188:191], v151 offset:33792
	ds_read_b128 v[192:195], v151 offset:34816
	ds_read_b128 v[196:199], v151 offset:35840
	ds_read_b128 v[200:203], v151 offset:36864
	ds_read_b128 v[204:207], v151 offset:37888
	ds_read_b128 v[208:211], v151 offset:38912
	ds_read_b128 v[216:219], v151 offset:39936
	global_load_lds_dwordx4 v[226:227], off
	v_lshl_add_u64 v[226:227], s[40:41], 0, v[134:135]
	s_mov_b32 m0, s54
	s_nop 0
	global_load_lds_dwordx4 v[226:227], off
	s_waitcnt vmcnt(8)
	s_waitcnt lgkmcnt(0)
	s_barrier
	s_waitcnt lgkmcnt(0)
	v_mfma_f32_16x16x32_bf16 v[82:85], v[152:155], v[184:187], v[82:85]
	v_mfma_f32_16x16x32_bf16 v[74:77], v[160:163], v[184:187], v[74:77]
	v_mfma_f32_16x16x32_bf16 v[70:73], v[152:155], v[192:195], v[70:73]
	v_mfma_f32_16x16x32_bf16 v[62:65], v[160:163], v[192:195], v[62:65]
	v_mfma_f32_16x16x32_bf16 v[54:57], v[152:155], v[200:203], v[54:57]
	v_mfma_f32_16x16x32_bf16 v[50:53], v[160:163], v[200:203], v[50:53]
	v_mfma_f32_16x16x32_bf16 v[38:41], v[152:155], v[208:211], v[38:41]
	v_mfma_f32_16x16x32_bf16 v[34:37], v[160:163], v[208:211], v[34:37]
	v_mfma_f32_16x16x32_bf16 v[82:85], v[156:159], v[188:191], v[82:85]
	v_mfma_f32_16x16x32_bf16 v[74:77], v[164:167], v[188:191], v[74:77]
	v_mfma_f32_16x16x32_bf16 v[70:73], v[156:159], v[196:199], v[70:73]
	v_mfma_f32_16x16x32_bf16 v[62:65], v[164:167], v[196:199], v[62:65]
	v_mfma_f32_16x16x32_bf16 v[54:57], v[156:159], v[204:207], v[54:57]
	v_mfma_f32_16x16x32_bf16 v[50:53], v[164:167], v[204:207], v[50:53]
	v_mfma_f32_16x16x32_bf16 v[38:41], v[156:159], v[216:219], v[38:41]
	v_mfma_f32_16x16x32_bf16 v[34:37], v[164:167], v[216:219], v[34:37]
	v_mfma_f32_16x16x32_bf16 v[126:129], v[168:171], v[184:187], v[126:129]
	v_mfma_f32_16x16x32_bf16 v[122:125], v[176:179], v[184:187], v[122:125]
	v_mfma_f32_16x16x32_bf16 v[118:121], v[168:171], v[192:195], v[118:121]
	v_mfma_f32_16x16x32_bf16 v[114:117], v[176:179], v[192:195], v[114:117]
	v_mfma_f32_16x16x32_bf16 v[110:113], v[168:171], v[200:203], v[110:113]
	v_mfma_f32_16x16x32_bf16 v[106:109], v[176:179], v[200:203], v[106:109]
	v_mfma_f32_16x16x32_bf16 v[102:105], v[168:171], v[208:211], v[102:105]
	v_mfma_f32_16x16x32_bf16 v[98:101], v[176:179], v[208:211], v[98:101]
	v_mfma_f32_16x16x32_bf16 v[126:129], v[172:175], v[188:191], v[126:129]
	v_mfma_f32_16x16x32_bf16 v[122:125], v[180:183], v[188:191], v[122:125]
	v_mfma_f32_16x16x32_bf16 v[118:121], v[172:175], v[196:199], v[118:121]
	v_mfma_f32_16x16x32_bf16 v[114:117], v[180:183], v[196:199], v[114:117]
	v_mfma_f32_16x16x32_bf16 v[110:113], v[172:175], v[204:207], v[110:113]
	v_mfma_f32_16x16x32_bf16 v[106:109], v[180:183], v[204:207], v[106:109]
	v_mfma_f32_16x16x32_bf16 v[102:105], v[172:175], v[216:219], v[102:105]
	v_mfma_f32_16x16x32_bf16 v[98:101], v[180:183], v[216:219], v[98:101]
	s_barrier
	s_add_i32 s40, s68, s50
	v_lshl_add_u64 v[212:213], v[212:213], 0, s[18:19]
	s_mov_b32 m0, s40
	ds_read_b128 v[184:187], v151 offset:49152
	ds_read_b128 v[188:191], v151 offset:50176
	ds_read_b128 v[192:195], v151 offset:51200
	ds_read_b128 v[196:199], v151 offset:52224
	ds_read_b128 v[200:203], v151 offset:53248
	ds_read_b128 v[204:207], v151 offset:54272
	ds_read_b128 v[208:211], v151 offset:55296
	ds_read_b128 v[216:219], v151 offset:56320
	global_load_lds_dwordx4 v[212:213], off
	s_add_i32 m0, s40, 0x2000
	s_add_u32 s36, s36, 0x100080
	v_lshl_add_u64 v[212:213], v[220:221], 0, s[18:19]
	s_addc_u32 s37, s37, 0
	s_add_i32 s40, s69, s50
	global_load_lds_dwordx4 v[212:213], off
	v_lshl_add_u64 v[212:213], s[36:37], 0, v[130:131]
	s_mov_b32 m0, s40
	s_nop 0
	global_load_lds_dwordx4 v[212:213], off
	v_lshl_add_u64 v[212:213], s[36:37], 0, v[132:133]
	s_add_i32 m0, s40, 0x2000
	s_nop 0
	global_load_lds_dwordx4 v[212:213], off
	v_lshl_add_u64 v[212:213], v[222:223], 0, s[18:19]
	s_mov_b32 m0, s30
	s_nop 0
	global_load_lds_dwordx4 v[212:213], off
	v_lshl_add_u64 v[212:213], v[224:225], 0, s[18:19]
	s_mov_b32 m0, s55
	s_nop 0
	global_load_lds_dwordx4 v[212:213], off
	s_waitcnt vmcnt(8)
	s_waitcnt lgkmcnt(0)
	s_barrier
	s_waitcnt lgkmcnt(0)
	v_mfma_f32_16x16x32_bf16 v[30:33], v[152:155], v[184:187], v[30:33]
	v_mfma_f32_16x16x32_bf16 v[26:29], v[160:163], v[184:187], v[26:29]
	v_mfma_f32_16x16x32_bf16 v[22:25], v[152:155], v[192:195], v[22:25]
	v_mfma_f32_16x16x32_bf16 v[18:21], v[160:163], v[192:195], v[18:21]
	v_mfma_f32_16x16x32_bf16 v[14:17], v[152:155], v[200:203], v[14:17]
	v_mfma_f32_16x16x32_bf16 v[10:13], v[160:163], v[200:203], v[10:13]
	v_mfma_f32_16x16x32_bf16 v[6:9], v[152:155], v[208:211], v[6:9]
	v_mfma_f32_16x16x32_bf16 v[2:5], v[160:163], v[208:211], v[2:5]
	v_mfma_f32_16x16x32_bf16 v[30:33], v[156:159], v[188:191], v[30:33]
	v_mfma_f32_16x16x32_bf16 v[26:29], v[164:167], v[188:191], v[26:29]
	v_mfma_f32_16x16x32_bf16 v[22:25], v[156:159], v[196:199], v[22:25]
	v_mfma_f32_16x16x32_bf16 v[18:21], v[164:167], v[196:199], v[18:21]
	v_mfma_f32_16x16x32_bf16 v[14:17], v[156:159], v[204:207], v[14:17]
	v_mfma_f32_16x16x32_bf16 v[10:13], v[164:167], v[204:207], v[10:13]
	v_mfma_f32_16x16x32_bf16 v[6:9], v[156:159], v[216:219], v[6:9]
	v_mfma_f32_16x16x32_bf16 v[2:5], v[164:167], v[216:219], v[2:5]
	v_mfma_f32_16x16x32_bf16 v[94:97], v[168:171], v[184:187], v[94:97]
	v_mfma_f32_16x16x32_bf16 v[90:93], v[176:179], v[184:187], v[90:93]
	v_mfma_f32_16x16x32_bf16 v[86:89], v[168:171], v[192:195], v[86:89]
	v_mfma_f32_16x16x32_bf16 v[78:81], v[176:179], v[192:195], v[78:81]
	v_mfma_f32_16x16x32_bf16 v[66:69], v[168:171], v[200:203], v[66:69]
	v_mfma_f32_16x16x32_bf16 v[58:61], v[176:179], v[200:203], v[58:61]
	v_mfma_f32_16x16x32_bf16 v[46:49], v[168:171], v[208:211], v[46:49]
	v_mfma_f32_16x16x32_bf16 v[42:45], v[176:179], v[208:211], v[42:45]
	v_mfma_f32_16x16x32_bf16 v[94:97], v[172:175], v[188:191], v[94:97]
	v_mfma_f32_16x16x32_bf16 v[90:93], v[180:183], v[188:191], v[90:93]
	v_mfma_f32_16x16x32_bf16 v[86:89], v[172:175], v[196:199], v[86:89]
	v_mfma_f32_16x16x32_bf16 v[78:81], v[180:183], v[196:199], v[78:81]
	v_mfma_f32_16x16x32_bf16 v[66:69], v[172:175], v[204:207], v[66:69]
	v_mfma_f32_16x16x32_bf16 v[58:61], v[180:183], v[204:207], v[58:61]
	v_mfma_f32_16x16x32_bf16 v[46:49], v[172:175], v[216:219], v[46:49]
	v_mfma_f32_16x16x32_bf16 v[42:45], v[180:183], v[216:219], v[42:45]
	s_add_i32 s67, s67, 2
	s_add_u32 s34, s34, 0x100
	s_addc_u32 s35, s35, 0
	s_add_u32 s63, s63, 0x100
	s_addc_u32 s66, s66, 0
	s_cmp_gt_u32 s67, 61
	s_barrier
	s_cbranch_scc0 .LBB0_132
	s_and_b64 vcc, exec, s[12:13]
	s_cbranch_vccz .LBB0_135
	s_barrier

.LBB0_872:
	s_add_u32 s26, s24, 0xfff00080
	s_addc_u32 s27, s25, -1
	s_add_i32 s56, 0, 0x10000
	s_cmp_eq_u32 s55, 60
	s_cselect_b32 s29, s13, s27
	s_cselect_b32 s28, s51, s26
	v_add_u32_e32 v148, s56, v152
	s_cselect_b32 s27, s9, s54
	s_cselect_b32 s26, s52, s53
	s_add_i32 s58, 0, 0x14000
	ds_read_b128 v[144:147], v148
	ds_read_b128 v[156:159], v148 offset:1024
	ds_read_b128 v[160:163], v148 offset:2048
	ds_read_b128 v[164:167], v148 offset:3072
	v_add_u32_e32 v148, s58, v152
	ds_read_b128 v[168:171], v148
	ds_read_b128 v[172:175], v148 offset:1024
	ds_read_b128 v[176:179], v148 offset:2048
	ds_read_b128 v[180:183], v148 offset:3072
	v_lshl_add_u64 v[148:149], s[24:25], 0, v[140:141]
	s_add_i32 m0, s41, 0xc000
	ds_read_b128 v[184:187], v154
	ds_read_b128 v[188:191], v154 offset:1024
	ds_read_b128 v[192:195], v154 offset:2048
	ds_read_b128 v[196:199], v154 offset:3072
	ds_read_b128 v[200:203], v154 offset:4096
	ds_read_b128 v[204:207], v154 offset:5120
	ds_read_b128 v[208:211], v154 offset:6144
	ds_read_b128 v[216:219], v154 offset:7168
	global_load_lds_dwordx4 v[148:149], off
	v_lshl_add_u64 v[148:149], s[24:25], 0, v[142:143]
	s_add_i32 m0, s41, 0xe000
	s_nop 0
	global_load_lds_dwordx4 v[148:149], off
	s_waitcnt vmcnt(8)
	s_waitcnt lgkmcnt(0)
	s_barrier
	s_waitcnt lgkmcnt(0)
	v_mfma_f32_16x16x32_bf16 v[126:129], v[144:147], v[184:187], v[126:129]
	v_mfma_f32_16x16x32_bf16 v[122:125], v[160:163], v[184:187], v[122:125]
	v_mfma_f32_16x16x32_bf16 v[110:113], v[144:147], v[192:195], v[110:113]
	v_mfma_f32_16x16x32_bf16 v[106:109], v[160:163], v[192:195], v[106:109]
	v_mfma_f32_16x16x32_bf16 v[94:97], v[144:147], v[200:203], v[94:97]
	v_mfma_f32_16x16x32_bf16 v[90:93], v[160:163], v[200:203], v[90:93]
	v_mfma_f32_16x16x32_bf16 v[78:81], v[144:147], v[208:211], v[78:81]
	v_mfma_f32_16x16x32_bf16 v[74:77], v[160:163], v[208:211], v[74:77]
	v_mfma_f32_16x16x32_bf16 v[126:129], v[156:159], v[188:191], v[126:129]
	v_mfma_f32_16x16x32_bf16 v[122:125], v[164:167], v[188:191], v[122:125]
	v_mfma_f32_16x16x32_bf16 v[110:113], v[156:159], v[196:199], v[110:113]
	v_mfma_f32_16x16x32_bf16 v[106:109], v[164:167], v[196:199], v[106:109]
	v_mfma_f32_16x16x32_bf16 v[94:97], v[156:159], v[204:207], v[94:97]
	v_mfma_f32_16x16x32_bf16 v[90:93], v[164:167], v[204:207], v[90:93]
	v_mfma_f32_16x16x32_bf16 v[78:81], v[156:159], v[216:219], v[78:81]
	v_mfma_f32_16x16x32_bf16 v[74:77], v[164:167], v[216:219], v[74:77]
	v_mfma_f32_16x16x32_bf16 v[118:121], v[168:171], v[184:187], v[118:121]
	v_mfma_f32_16x16x32_bf16 v[114:117], v[176:179], v[184:187], v[114:117]
	v_mfma_f32_16x16x32_bf16 v[102:105], v[168:171], v[192:195], v[102:105]
	v_mfma_f32_16x16x32_bf16 v[98:101], v[176:179], v[192:195], v[98:101]
	v_mfma_f32_16x16x32_bf16 v[86:89], v[168:171], v[200:203], v[86:89]
	v_mfma_f32_16x16x32_bf16 v[82:85], v[176:179], v[200:203], v[82:85]
	v_mfma_f32_16x16x32_bf16 v[70:73], v[168:171], v[208:211], v[70:73]
	v_mfma_f32_16x16x32_bf16 v[66:69], v[176:179], v[208:211], v[66:69]
	v_mfma_f32_16x16x32_bf16 v[118:121], v[172:175], v[188:191], v[118:121]
	v_mfma_f32_16x16x32_bf16 v[114:117], v[180:183], v[188:191], v[114:117]
	v_mfma_f32_16x16x32_bf16 v[102:105], v[172:175], v[196:199], v[102:105]
	v_mfma_f32_16x16x32_bf16 v[98:101], v[180:183], v[196:199], v[98:101]
	v_mfma_f32_16x16x32_bf16 v[86:89], v[172:175], v[204:207], v[86:89]
	v_mfma_f32_16x16x32_bf16 v[82:85], v[180:183], v[204:207], v[82:85]
	v_mfma_f32_16x16x32_bf16 v[70:73], v[172:175], v[216:219], v[70:73]
	v_mfma_f32_16x16x32_bf16 v[66:69], v[180:183], v[216:219], v[66:69]
	s_barrier
	s_add_i32 s56, s56, s40
	v_lshl_add_u64 v[148:149], s[26:27], 0, v[130:131]
	s_mov_b32 m0, s56
	ds_read_b128 v[184:187], v154 offset:16384
	ds_read_b128 v[188:191], v154 offset:17408
	ds_read_b128 v[192:195], v154 offset:18432
	ds_read_b128 v[196:199], v154 offset:19456
	ds_read_b128 v[200:203], v154 offset:20480
	ds_read_b128 v[204:207], v154 offset:21504
	ds_read_b128 v[208:211], v154 offset:22528
	ds_read_b128 v[216:219], v154 offset:23552
	global_load_lds_dwordx4 v[148:149], off
	s_add_i32 m0, s56, 0x2000
	s_add_u32 s56, s26, 0x100000
	v_lshl_add_u64 v[212:213], s[26:27], 0, v[132:133]
	s_addc_u32 s57, s27, 0
	s_add_i32 s58, s58, s40
	global_load_lds_dwordx4 v[212:213], off
	v_lshl_add_u64 v[220:221], s[56:57], 0, v[130:131]
	s_mov_b32 m0, s58
	v_lshl_add_u64 v[222:223], s[28:29], 0, v[134:135]
	global_load_lds_dwordx4 v[220:221], off
	v_lshl_add_u64 v[220:221], s[56:57], 0, v[132:133]
	s_add_i32 m0, s58, 0x2000
	s_nop 0
	global_load_lds_dwordx4 v[220:221], off
	v_lshl_add_u64 v[220:221], s[28:29], 0, v[136:137]
	s_mov_b32 m0, s41
	s_nop 0
	global_load_lds_dwordx4 v[220:221], off
	s_mov_b32 m0, s44
	s_nop 0
	global_load_lds_dwordx4 v[222:223], off
	s_waitcnt vmcnt(8)
	s_waitcnt lgkmcnt(0)
	s_barrier
	s_waitcnt lgkmcnt(0)
	v_mfma_f32_16x16x32_bf16 v[62:65], v[144:147], v[184:187], v[62:65]
	v_mfma_f32_16x16x32_bf16 v[58:61], v[160:163], v[184:187], v[58:61]
	v_mfma_f32_16x16x32_bf16 v[46:49], v[144:147], v[192:195], v[46:49]
	v_mfma_f32_16x16x32_bf16 v[42:45], v[160:163], v[192:195], v[42:45]
	v_mfma_f32_16x16x32_bf16 v[30:33], v[144:147], v[200:203], v[30:33]
	v_mfma_f32_16x16x32_bf16 v[26:29], v[160:163], v[200:203], v[26:29]
	v_mfma_f32_16x16x32_bf16 v[14:17], v[144:147], v[208:211], v[14:17]
	v_mfma_f32_16x16x32_bf16 v[10:13], v[160:163], v[208:211], v[10:13]
	v_mfma_f32_16x16x32_bf16 v[62:65], v[156:159], v[188:191], v[62:65]
	v_mfma_f32_16x16x32_bf16 v[58:61], v[164:167], v[188:191], v[58:61]
	v_mfma_f32_16x16x32_bf16 v[46:49], v[156:159], v[196:199], v[46:49]
	v_mfma_f32_16x16x32_bf16 v[42:45], v[164:167], v[196:199], v[42:45]
	v_mfma_f32_16x16x32_bf16 v[30:33], v[156:159], v[204:207], v[30:33]
	v_mfma_f32_16x16x32_bf16 v[26:29], v[164:167], v[204:207], v[26:29]
	v_mfma_f32_16x16x32_bf16 v[14:17], v[156:159], v[216:219], v[14:17]
	v_mfma_f32_16x16x32_bf16 v[10:13], v[164:167], v[216:219], v[10:13]
	v_mfma_f32_16x16x32_bf16 v[54:57], v[168:171], v[184:187], v[54:57]
	v_mfma_f32_16x16x32_bf16 v[50:53], v[176:179], v[184:187], v[50:53]
	v_mfma_f32_16x16x32_bf16 v[38:41], v[168:171], v[192:195], v[38:41]
	v_mfma_f32_16x16x32_bf16 v[34:37], v[176:179], v[192:195], v[34:37]
	v_mfma_f32_16x16x32_bf16 v[22:25], v[168:171], v[200:203], v[22:25]
	v_mfma_f32_16x16x32_bf16 v[18:21], v[176:179], v[200:203], v[18:21]
	v_mfma_f32_16x16x32_bf16 v[6:9], v[168:171], v[208:211], v[6:9]
	v_mfma_f32_16x16x32_bf16 v[2:5], v[176:179], v[208:211], v[2:5]
	v_mfma_f32_16x16x32_bf16 v[54:57], v[172:175], v[188:191], v[54:57]
	v_mfma_f32_16x16x32_bf16 v[50:53], v[180:183], v[188:191], v[50:53]
	v_mfma_f32_16x16x32_bf16 v[38:41], v[172:175], v[196:199], v[38:41]
	v_mfma_f32_16x16x32_bf16 v[34:37], v[180:183], v[196:199], v[34:37]
	v_mfma_f32_16x16x32_bf16 v[22:25], v[172:175], v[204:207], v[22:25]
	v_mfma_f32_16x16x32_bf16 v[18:21], v[180:183], v[204:207], v[18:21]
	v_mfma_f32_16x16x32_bf16 v[6:9], v[172:175], v[216:219], v[6:9]
	v_mfma_f32_16x16x32_bf16 v[2:5], v[180:183], v[216:219], v[2:5]
	s_barrier
	s_add_i32 s56, 0, 0x18000
	v_add_u32_e32 v155, s56, v152
	s_add_i32 s57, 0, 0x1c000
	ds_read_b128 v[144:147], v155
	ds_read_b128 v[156:159], v155 offset:1024
	ds_read_b128 v[160:163], v155 offset:2048
	ds_read_b128 v[164:167], v155 offset:3072
	v_add_u32_e32 v155, s57, v152
	ds_read_b128 v[168:171], v155
	ds_read_b128 v[172:175], v155 offset:1024
	ds_read_b128 v[176:179], v155 offset:2048
	ds_read_b128 v[180:183], v155 offset:3072
	s_add_u32 s28, s28, 0x100000
	s_addc_u32 s29, s29, 0
	s_mov_b32 m0, s45
	v_lshl_add_u64 v[224:225], s[28:29], 0, v[136:137]
	ds_read_b128 v[184:187], v154 offset:32768
	ds_read_b128 v[188:191], v154 offset:33792
	ds_read_b128 v[192:195], v154 offset:34816
	ds_read_b128 v[196:199], v154 offset:35840
	ds_read_b128 v[200:203], v154 offset:36864
	ds_read_b128 v[204:207], v154 offset:37888
	ds_read_b128 v[208:211], v154 offset:38912
	ds_read_b128 v[216:219], v154 offset:39936
	global_load_lds_dwordx4 v[224:225], off
	v_lshl_add_u64 v[224:225], s[28:29], 0, v[134:135]
	s_mov_b32 m0, s46
	s_nop 0
	global_load_lds_dwordx4 v[224:225], off
	s_waitcnt vmcnt(8)
	s_waitcnt lgkmcnt(0)
	s_barrier
	s_waitcnt lgkmcnt(0)
	v_mfma_f32_16x16x32_bf16 v[126:129], v[144:147], v[184:187], v[126:129]
	v_mfma_f32_16x16x32_bf16 v[122:125], v[160:163], v[184:187], v[122:125]
	v_mfma_f32_16x16x32_bf16 v[110:113], v[144:147], v[192:195], v[110:113]
	v_mfma_f32_16x16x32_bf16 v[106:109], v[160:163], v[192:195], v[106:109]
	v_mfma_f32_16x16x32_bf16 v[94:97], v[144:147], v[200:203], v[94:97]
	v_mfma_f32_16x16x32_bf16 v[90:93], v[160:163], v[200:203], v[90:93]
	v_mfma_f32_16x16x32_bf16 v[78:81], v[144:147], v[208:211], v[78:81]
	v_mfma_f32_16x16x32_bf16 v[74:77], v[160:163], v[208:211], v[74:77]
	v_mfma_f32_16x16x32_bf16 v[126:129], v[156:159], v[188:191], v[126:129]
	v_mfma_f32_16x16x32_bf16 v[122:125], v[164:167], v[188:191], v[122:125]
	v_mfma_f32_16x16x32_bf16 v[110:113], v[156:159], v[196:199], v[110:113]
	v_mfma_f32_16x16x32_bf16 v[106:109], v[164:167], v[196:199], v[106:109]
	v_mfma_f32_16x16x32_bf16 v[94:97], v[156:159], v[204:207], v[94:97]
	v_mfma_f32_16x16x32_bf16 v[90:93], v[164:167], v[204:207], v[90:93]
	v_mfma_f32_16x16x32_bf16 v[78:81], v[156:159], v[216:219], v[78:81]
	v_mfma_f32_16x16x32_bf16 v[74:77], v[164:167], v[216:219], v[74:77]
	v_mfma_f32_16x16x32_bf16 v[118:121], v[168:171], v[184:187], v[118:121]
	v_mfma_f32_16x16x32_bf16 v[114:117], v[176:179], v[184:187], v[114:117]
	v_mfma_f32_16x16x32_bf16 v[102:105], v[168:171], v[192:195], v[102:105]
	v_mfma_f32_16x16x32_bf16 v[98:101], v[176:179], v[192:195], v[98:101]
	v_mfma_f32_16x16x32_bf16 v[86:89], v[168:171], v[200:203], v[86:89]
	v_mfma_f32_16x16x32_bf16 v[82:85], v[176:179], v[200:203], v[82:85]
	v_mfma_f32_16x16x32_bf16 v[70:73], v[168:171], v[208:211], v[70:73]
	v_mfma_f32_16x16x32_bf16 v[66:69], v[176:179], v[208:211], v[66:69]
	v_mfma_f32_16x16x32_bf16 v[118:121], v[172:175], v[188:191], v[118:121]
	v_mfma_f32_16x16x32_bf16 v[114:117], v[180:183], v[188:191], v[114:117]
	v_mfma_f32_16x16x32_bf16 v[102:105], v[172:175], v[196:199], v[102:105]
	v_mfma_f32_16x16x32_bf16 v[98:101], v[180:183], v[196:199], v[98:101]
	v_mfma_f32_16x16x32_bf16 v[86:89], v[172:175], v[204:207], v[86:89]
	v_mfma_f32_16x16x32_bf16 v[82:85], v[180:183], v[204:207], v[82:85]
	v_mfma_f32_16x16x32_bf16 v[70:73], v[172:175], v[216:219], v[70:73]
	v_mfma_f32_16x16x32_bf16 v[66:69], v[180:183], v[216:219], v[66:69]
	s_barrier
	s_add_i32 s28, s56, s40
	v_lshl_add_u64 v[148:149], v[148:149], 0, s[18:19]
	s_mov_b32 m0, s28
	ds_read_b128 v[184:187], v154 offset:49152
	ds_read_b128 v[188:191], v154 offset:50176
	ds_read_b128 v[192:195], v154 offset:51200
	ds_read_b128 v[196:199], v154 offset:52224
	ds_read_b128 v[200:203], v154 offset:53248
	ds_read_b128 v[204:207], v154 offset:54272
	ds_read_b128 v[208:211], v154 offset:55296
	ds_read_b128 v[216:219], v154 offset:56320
	global_load_lds_dwordx4 v[148:149], off
	s_add_i32 m0, s28, 0x2000
	s_add_u32 s26, s26, 0x100080
	v_lshl_add_u64 v[148:149], v[212:213], 0, s[18:19]
	s_addc_u32 s27, s27, 0
	s_add_i32 s28, s57, s40
	global_load_lds_dwordx4 v[148:149], off
	v_lshl_add_u64 v[148:149], s[26:27], 0, v[130:131]
	s_mov_b32 m0, s28
	s_nop 0
	global_load_lds_dwordx4 v[148:149], off
	v_lshl_add_u64 v[148:149], s[26:27], 0, v[132:133]
	s_add_i32 m0, s28, 0x2000
	s_nop 0
	global_load_lds_dwordx4 v[148:149], off
	v_lshl_add_u64 v[148:149], v[220:221], 0, s[18:19]
	s_mov_b32 m0, s30
	s_nop 0
	global_load_lds_dwordx4 v[148:149], off
	v_lshl_add_u64 v[148:149], v[222:223], 0, s[18:19]
	s_mov_b32 m0, s47
	s_nop 0
	global_load_lds_dwordx4 v[148:149], off
	s_waitcnt vmcnt(8)
	s_waitcnt lgkmcnt(0)
	s_barrier
	s_waitcnt lgkmcnt(0)
	v_mfma_f32_16x16x32_bf16 v[62:65], v[144:147], v[184:187], v[62:65]
	v_mfma_f32_16x16x32_bf16 v[58:61], v[160:163], v[184:187], v[58:61]
	v_mfma_f32_16x16x32_bf16 v[46:49], v[144:147], v[192:195], v[46:49]
	v_mfma_f32_16x16x32_bf16 v[42:45], v[160:163], v[192:195], v[42:45]
	v_mfma_f32_16x16x32_bf16 v[30:33], v[144:147], v[200:203], v[30:33]
	v_mfma_f32_16x16x32_bf16 v[26:29], v[160:163], v[200:203], v[26:29]
	v_mfma_f32_16x16x32_bf16 v[14:17], v[144:147], v[208:211], v[14:17]
	v_mfma_f32_16x16x32_bf16 v[10:13], v[160:163], v[208:211], v[10:13]
	v_mfma_f32_16x16x32_bf16 v[62:65], v[156:159], v[188:191], v[62:65]
	v_mfma_f32_16x16x32_bf16 v[58:61], v[164:167], v[188:191], v[58:61]
	v_mfma_f32_16x16x32_bf16 v[46:49], v[156:159], v[196:199], v[46:49]
	v_mfma_f32_16x16x32_bf16 v[42:45], v[164:167], v[196:199], v[42:45]
	v_mfma_f32_16x16x32_bf16 v[30:33], v[156:159], v[204:207], v[30:33]
	v_mfma_f32_16x16x32_bf16 v[26:29], v[164:167], v[204:207], v[26:29]
	v_mfma_f32_16x16x32_bf16 v[14:17], v[156:159], v[216:219], v[14:17]
	v_mfma_f32_16x16x32_bf16 v[10:13], v[164:167], v[216:219], v[10:13]
	v_mfma_f32_16x16x32_bf16 v[54:57], v[168:171], v[184:187], v[54:57]
	v_mfma_f32_16x16x32_bf16 v[50:53], v[176:179], v[184:187], v[50:53]
	v_mfma_f32_16x16x32_bf16 v[38:41], v[168:171], v[192:195], v[38:41]
	v_mfma_f32_16x16x32_bf16 v[34:37], v[176:179], v[192:195], v[34:37]
	v_mfma_f32_16x16x32_bf16 v[22:25], v[168:171], v[200:203], v[22:25]
	v_mfma_f32_16x16x32_bf16 v[18:21], v[176:179], v[200:203], v[18:21]
	v_mfma_f32_16x16x32_bf16 v[6:9], v[168:171], v[208:211], v[6:9]
	v_mfma_f32_16x16x32_bf16 v[2:5], v[176:179], v[208:211], v[2:5]
	v_mfma_f32_16x16x32_bf16 v[54:57], v[172:175], v[188:191], v[54:57]
	v_mfma_f32_16x16x32_bf16 v[50:53], v[180:183], v[188:191], v[50:53]
	v_mfma_f32_16x16x32_bf16 v[38:41], v[172:175], v[196:199], v[38:41]
	v_mfma_f32_16x16x32_bf16 v[34:37], v[180:183], v[196:199], v[34:37]
	v_mfma_f32_16x16x32_bf16 v[22:25], v[172:175], v[204:207], v[22:25]
	v_mfma_f32_16x16x32_bf16 v[18:21], v[180:183], v[204:207], v[18:21]
	v_mfma_f32_16x16x32_bf16 v[6:9], v[172:175], v[216:219], v[6:9]
	v_mfma_f32_16x16x32_bf16 v[2:5], v[180:183], v[216:219], v[2:5]
	s_add_i32 s55, s55, 2
	s_add_u32 s24, s24, 0x100
	s_addc_u32 s25, s25, 0
	s_add_u32 s53, s53, 0x100
	s_addc_u32 s54, s54, 0
	s_cmp_gt_u32 s55, 61
	s_barrier
	s_cbranch_scc0 .LBB0_872
	s_and_b64 vcc, exec, s[6:7]
	s_cbranch_vccz .LBB0_875
	s_barrier

.LBB0_1024:
	s_add_u32 s46, s2, 0xfff00080
	s_addc_u32 s47, s3, -1
	s_add_i32 s83, 0, 0x10000
	s_cmp_eq_u32 s82, 60
	s_cselect_b32 s59, s30, s47
	s_cselect_b32 s58, s53, s46
	s_cselect_b32 s47, s51, s81
	s_cselect_b32 s46, s79, s80
	s_add_i32 s86, 0, 0x14000
	v_add_u32_e32 v74, s83, v244
	v_add_u32_e32 v94, s86, v244
	ds_read_b128 v[62:65], v74
	ds_read_b128 v[66:69], v74 offset:1024
	ds_read_b128 v[70:73], v74 offset:2048
	ds_read_b128 v[74:77], v74 offset:3072
	ds_read_b128 v[78:81], v94
	ds_read_b128 v[82:85], v94 offset:1024
	ds_read_b128 v[90:93], v94 offset:2048
	ds_read_b128 v[94:97], v94 offset:3072
	v_lshl_add_u64 v[196:197], s[2:3], 0, v[222:223]
	s_add_i32 m0, s67, 0xc000
	ds_read_b128 v[98:101], v250
	ds_read_b128 v[102:105], v250 offset:1024
	ds_read_b128 v[106:109], v250 offset:2048
	ds_read_b128 v[110:113], v250 offset:3072
	ds_read_b128 v[180:183], v250 offset:4096
	ds_read_b128 v[184:187], v250 offset:5120
	ds_read_b128 v[188:191], v250 offset:6144
	ds_read_b128 v[192:195], v250 offset:7168
	global_load_lds_dwordx4 v[196:197], off
	v_lshl_add_u64 v[196:197], s[2:3], 0, v[224:225]
	s_add_i32 m0, s67, 0xe000
	s_nop 0
	global_load_lds_dwordx4 v[196:197], off
	s_waitcnt vmcnt(8)
	s_waitcnt lgkmcnt(0)
	s_barrier
	s_waitcnt lgkmcnt(0)
	v_mfma_f32_16x16x32_bf16 v[176:179], v[62:65], v[98:101], v[176:179]
	v_mfma_f32_16x16x32_bf16 v[168:171], v[70:73], v[98:101], v[168:171]
	v_mfma_f32_16x16x32_bf16 v[160:163], v[62:65], v[106:109], v[160:163]
	v_mfma_f32_16x16x32_bf16 v[152:155], v[70:73], v[106:109], v[152:155]
	v_mfma_f32_16x16x32_bf16 v[144:147], v[62:65], v[180:183], v[144:147]
	v_mfma_f32_16x16x32_bf16 v[136:139], v[70:73], v[180:183], v[136:139]
	v_mfma_f32_16x16x32_bf16 v[126:129], v[62:65], v[188:191], v[126:129]
	v_mfma_f32_16x16x32_bf16 v[118:121], v[70:73], v[188:191], v[118:121]
	v_mfma_f32_16x16x32_bf16 v[176:179], v[66:69], v[102:105], v[176:179]
	v_mfma_f32_16x16x32_bf16 v[168:171], v[74:77], v[102:105], v[168:171]
	v_mfma_f32_16x16x32_bf16 v[160:163], v[66:69], v[110:113], v[160:163]
	v_mfma_f32_16x16x32_bf16 v[152:155], v[74:77], v[110:113], v[152:155]
	v_mfma_f32_16x16x32_bf16 v[144:147], v[66:69], v[184:187], v[144:147]
	v_mfma_f32_16x16x32_bf16 v[136:139], v[74:77], v[184:187], v[136:139]
	v_mfma_f32_16x16x32_bf16 v[126:129], v[66:69], v[192:195], v[126:129]
	v_mfma_f32_16x16x32_bf16 v[118:121], v[74:77], v[192:195], v[118:121]
	v_mfma_f32_16x16x32_bf16 v[172:175], v[78:81], v[98:101], v[172:175]
	v_mfma_f32_16x16x32_bf16 v[98:101], v[90:93], v[98:101], v[164:167]
	v_mfma_f32_16x16x32_bf16 v[172:175], v[82:85], v[102:105], v[172:175]
	v_mfma_f32_16x16x32_bf16 v[98:101], v[94:97], v[102:105], v[98:101]
	v_mfma_f32_16x16x32_bf16 v[102:105], v[78:81], v[106:109], v[156:159]
	v_mfma_f32_16x16x32_bf16 v[106:109], v[90:93], v[106:109], v[148:151]
	v_mfma_f32_16x16x32_bf16 v[132:135], v[90:93], v[180:183], v[132:135]
	v_mfma_f32_16x16x32_bf16 v[122:125], v[78:81], v[188:191], v[122:125]
	v_mfma_f32_16x16x32_bf16 v[114:117], v[90:93], v[188:191], v[114:117]
	v_mfma_f32_16x16x32_bf16 v[102:105], v[82:85], v[110:113], v[102:105]
	v_mfma_f32_16x16x32_bf16 v[106:109], v[94:97], v[110:113], v[106:109]
	v_mfma_f32_16x16x32_bf16 v[110:113], v[78:81], v[180:183], v[140:143]
	v_mfma_f32_16x16x32_bf16 v[132:135], v[94:97], v[184:187], v[132:135]
	v_mfma_f32_16x16x32_bf16 v[122:125], v[82:85], v[192:195], v[122:125]
	v_mfma_f32_16x16x32_bf16 v[114:117], v[94:97], v[192:195], v[114:117]
	v_mfma_f32_16x16x32_bf16 v[110:113], v[82:85], v[184:187], v[110:113]
	s_barrier
	s_add_i32 s83, s83, s66
	v_lshl_add_u64 v[204:205], s[46:47], 0, v[130:131]
	s_mov_b32 m0, s83
	ds_read_b128 v[140:143], v250 offset:16384
	ds_read_b128 v[148:151], v250 offset:17408
	ds_read_b128 v[156:159], v250 offset:18432
	ds_read_b128 v[164:167], v250 offset:19456
	ds_read_b128 v[180:183], v250 offset:20480
	ds_read_b128 v[184:187], v250 offset:21504
	ds_read_b128 v[188:191], v250 offset:22528
	ds_read_b128 v[192:195], v250 offset:23552
	global_load_lds_dwordx4 v[204:205], off
	s_add_i32 m0, s83, 0x2000
	s_add_u32 s84, s46, 0x100000
	v_lshl_add_u64 v[206:207], s[46:47], 0, v[216:217]
	s_addc_u32 s85, s47, 0
	s_add_i32 s83, s86, s66
	global_load_lds_dwordx4 v[206:207], off
	v_lshl_add_u64 v[196:197], s[84:85], 0, v[130:131]
	s_mov_b32 m0, s83
	v_lshl_add_u64 v[208:209], s[58:59], 0, v[220:221]
	global_load_lds_dwordx4 v[196:197], off
	v_lshl_add_u64 v[196:197], s[84:85], 0, v[216:217]
	s_add_i32 m0, s83, 0x2000
	v_lshl_add_u64 v[210:211], s[58:59], 0, v[218:219]
	global_load_lds_dwordx4 v[196:197], off
	s_mov_b32 m0, s67
	s_nop 0
	global_load_lds_dwordx4 v[208:209], off
	s_mov_b32 m0, s68
	s_nop 0
	global_load_lds_dwordx4 v[210:211], off
	s_waitcnt vmcnt(8)
	s_waitcnt lgkmcnt(0)
	s_barrier
	s_waitcnt lgkmcnt(0)
	v_mfma_f32_16x16x32_bf16 v[86:89], v[62:65], v[140:143], v[86:89]
	v_mfma_f32_16x16x32_bf16 v[54:57], v[70:73], v[140:143], v[54:57]
	v_mfma_f32_16x16x32_bf16 v[46:49], v[62:65], v[156:159], v[46:49]
	v_mfma_f32_16x16x32_bf16 v[38:41], v[70:73], v[156:159], v[38:41]
	v_mfma_f32_16x16x32_bf16 v[30:33], v[62:65], v[180:183], v[30:33]
	v_mfma_f32_16x16x32_bf16 v[22:25], v[70:73], v[180:183], v[22:25]
	v_mfma_f32_16x16x32_bf16 v[14:17], v[62:65], v[188:191], v[14:17]
	v_mfma_f32_16x16x32_bf16 v[6:9], v[70:73], v[188:191], v[6:9]
	v_mfma_f32_16x16x32_bf16 v[86:89], v[66:69], v[148:151], v[86:89]
	v_mfma_f32_16x16x32_bf16 v[54:57], v[74:77], v[148:151], v[54:57]
	v_mfma_f32_16x16x32_bf16 v[46:49], v[66:69], v[164:167], v[46:49]
	v_mfma_f32_16x16x32_bf16 v[38:41], v[74:77], v[164:167], v[38:41]
	v_mfma_f32_16x16x32_bf16 v[30:33], v[66:69], v[184:187], v[30:33]
	v_mfma_f32_16x16x32_bf16 v[22:25], v[74:77], v[184:187], v[22:25]
	v_mfma_f32_16x16x32_bf16 v[14:17], v[66:69], v[192:195], v[14:17]
	v_mfma_f32_16x16x32_bf16 v[6:9], v[74:77], v[192:195], v[6:9]
	v_mfma_f32_16x16x32_bf16 v[58:61], v[78:81], v[140:143], v[58:61]
	v_mfma_f32_16x16x32_bf16 v[50:53], v[90:93], v[140:143], v[50:53]
	v_mfma_f32_16x16x32_bf16 v[42:45], v[78:81], v[156:159], v[42:45]
	v_mfma_f32_16x16x32_bf16 v[34:37], v[90:93], v[156:159], v[34:37]
	v_mfma_f32_16x16x32_bf16 v[26:29], v[78:81], v[180:183], v[26:29]
	v_mfma_f32_16x16x32_bf16 v[18:21], v[90:93], v[180:183], v[18:21]
	v_mfma_f32_16x16x32_bf16 v[10:13], v[78:81], v[188:191], v[10:13]
	v_mfma_f32_16x16x32_bf16 v[2:5], v[90:93], v[188:191], v[2:5]
	v_mfma_f32_16x16x32_bf16 v[58:61], v[82:85], v[148:151], v[58:61]
	v_mfma_f32_16x16x32_bf16 v[50:53], v[94:97], v[148:151], v[50:53]
	v_mfma_f32_16x16x32_bf16 v[42:45], v[82:85], v[164:167], v[42:45]
	v_mfma_f32_16x16x32_bf16 v[34:37], v[94:97], v[164:167], v[34:37]
	v_mfma_f32_16x16x32_bf16 v[26:29], v[82:85], v[184:187], v[26:29]
	v_mfma_f32_16x16x32_bf16 v[18:21], v[94:97], v[184:187], v[18:21]
	v_mfma_f32_16x16x32_bf16 v[10:13], v[82:85], v[192:195], v[10:13]
	v_mfma_f32_16x16x32_bf16 v[2:5], v[94:97], v[192:195], v[2:5]
	s_barrier
	s_add_i32 s83, 0, 0x18000
	s_add_i32 s84, 0, 0x1c000
	v_add_u32_e32 v74, s83, v244
	v_add_u32_e32 v94, s84, v244
	ds_read_b128 v[62:65], v74
	ds_read_b128 v[66:69], v74 offset:1024
	ds_read_b128 v[70:73], v74 offset:2048
	ds_read_b128 v[74:77], v74 offset:3072
	ds_read_b128 v[78:81], v94
	ds_read_b128 v[82:85], v94 offset:1024
	ds_read_b128 v[90:93], v94 offset:2048
	ds_read_b128 v[94:97], v94 offset:3072
	s_add_u32 s58, s58, 0x100000
	s_addc_u32 s59, s59, 0
	s_mov_b32 m0, s69
	v_lshl_add_u64 v[156:157], s[58:59], 0, v[220:221]
	ds_read_b128 v[140:143], v250 offset:32768
	ds_read_b128 v[148:151], v250 offset:33792
	ds_read_b128 v[180:183], v250 offset:34816
	ds_read_b128 v[184:187], v250 offset:35840
	ds_read_b128 v[188:191], v250 offset:36864
	ds_read_b128 v[192:195], v250 offset:37888
	ds_read_b128 v[196:199], v250 offset:38912
	ds_read_b128 v[200:203], v250 offset:39936
	global_load_lds_dwordx4 v[156:157], off
	v_lshl_add_u64 v[156:157], s[58:59], 0, v[218:219]
	s_mov_b32 m0, s70
	s_nop 0
	global_load_lds_dwordx4 v[156:157], off
	s_waitcnt vmcnt(8)
	s_waitcnt lgkmcnt(0)
	s_barrier
	s_waitcnt lgkmcnt(0)
	v_mfma_f32_16x16x32_bf16 v[156:159], v[62:65], v[140:143], v[176:179]
	v_mfma_f32_16x16x32_bf16 v[176:179], v[66:69], v[148:151], v[156:159]
	v_mfma_f32_16x16x32_bf16 v[156:159], v[70:73], v[140:143], v[168:171]
	v_mfma_f32_16x16x32_bf16 v[168:171], v[74:77], v[148:151], v[156:159]
	v_mfma_f32_16x16x32_bf16 v[156:159], v[62:65], v[180:183], v[160:163]
	v_mfma_f32_16x16x32_bf16 v[152:155], v[70:73], v[180:183], v[152:155]
	v_mfma_f32_16x16x32_bf16 v[144:147], v[62:65], v[188:191], v[144:147]
	v_mfma_f32_16x16x32_bf16 v[136:139], v[70:73], v[188:191], v[136:139]
	v_mfma_f32_16x16x32_bf16 v[126:129], v[62:65], v[196:199], v[126:129]
	v_mfma_f32_16x16x32_bf16 v[118:121], v[70:73], v[196:199], v[118:121]
	v_mfma_f32_16x16x32_bf16 v[160:163], v[66:69], v[184:187], v[156:159]
	v_mfma_f32_16x16x32_bf16 v[152:155], v[74:77], v[184:187], v[152:155]
	v_mfma_f32_16x16x32_bf16 v[144:147], v[66:69], v[192:195], v[144:147]
	v_mfma_f32_16x16x32_bf16 v[136:139], v[74:77], v[192:195], v[136:139]
	v_mfma_f32_16x16x32_bf16 v[126:129], v[66:69], v[200:203], v[126:129]
	v_mfma_f32_16x16x32_bf16 v[118:121], v[74:77], v[200:203], v[118:121]
	v_mfma_f32_16x16x32_bf16 v[98:101], v[90:93], v[140:143], v[98:101]
	v_mfma_f32_16x16x32_bf16 v[156:159], v[78:81], v[140:143], v[172:175]
	v_mfma_f32_16x16x32_bf16 v[164:167], v[94:97], v[148:151], v[98:101]
	v_mfma_f32_16x16x32_bf16 v[98:101], v[78:81], v[180:183], v[102:105]
	v_mfma_f32_16x16x32_bf16 v[172:175], v[82:85], v[148:151], v[156:159]
	v_mfma_f32_16x16x32_bf16 v[156:159], v[82:85], v[184:187], v[98:101]
	v_mfma_f32_16x16x32_bf16 v[98:101], v[90:93], v[180:183], v[106:109]
	v_mfma_f32_16x16x32_bf16 v[148:151], v[94:97], v[184:187], v[98:101]
	v_mfma_f32_16x16x32_bf16 v[98:101], v[78:81], v[188:191], v[110:113]
	v_mfma_f32_16x16x32_bf16 v[140:143], v[82:85], v[192:195], v[98:101]
	v_mfma_f32_16x16x32_bf16 v[98:101], v[90:93], v[188:191], v[132:135]
	v_mfma_f32_16x16x32_bf16 v[132:135], v[94:97], v[192:195], v[98:101]
	v_mfma_f32_16x16x32_bf16 v[98:101], v[78:81], v[196:199], v[122:125]
	v_mfma_f32_16x16x32_bf16 v[122:125], v[82:85], v[200:203], v[98:101]
	v_mfma_f32_16x16x32_bf16 v[98:101], v[90:93], v[196:199], v[114:117]
	v_mfma_f32_16x16x32_bf16 v[114:117], v[94:97], v[200:203], v[98:101]
	s_barrier
	s_add_i32 s58, s83, s66
	v_lshl_add_u64 v[196:197], v[204:205], 0, s[18:19]
	s_mov_b32 m0, s58
	s_nop 1
	ds_read_b128 v[98:101], v250 offset:49152
	ds_read_b128 v[102:105], v250 offset:50176
	ds_read_b128 v[106:109], v250 offset:51200
	ds_read_b128 v[110:113], v250 offset:52224
	ds_read_b128 v[180:183], v250 offset:53248
	ds_read_b128 v[184:187], v250 offset:54272
	ds_read_b128 v[188:191], v250 offset:55296
	ds_read_b128 v[192:195], v250 offset:56320
	global_load_lds_dwordx4 v[196:197], off
	s_add_i32 m0, s58, 0x2000
	s_add_u32 s46, s46, 0x100080
	v_lshl_add_u64 v[196:197], v[206:207], 0, s[18:19]
	s_addc_u32 s47, s47, 0
	s_add_i32 s58, s84, s66
	global_load_lds_dwordx4 v[196:197], off
	v_lshl_add_u64 v[196:197], s[46:47], 0, v[130:131]
	s_mov_b32 m0, s58
	s_nop 0
	global_load_lds_dwordx4 v[196:197], off
	v_lshl_add_u64 v[196:197], s[46:47], 0, v[216:217]
	s_add_i32 m0, s58, 0x2000
	s_nop 0
	global_load_lds_dwordx4 v[196:197], off
	v_lshl_add_u64 v[196:197], v[208:209], 0, s[18:19]
	s_mov_b32 m0, s74
	s_nop 0
	global_load_lds_dwordx4 v[196:197], off
	v_lshl_add_u64 v[196:197], v[210:211], 0, s[18:19]
	s_mov_b32 m0, s75
	s_nop 0
	global_load_lds_dwordx4 v[196:197], off
	s_waitcnt vmcnt(8)
	s_waitcnt lgkmcnt(0)
	s_barrier
	s_waitcnt lgkmcnt(0)
	v_mfma_f32_16x16x32_bf16 v[86:89], v[62:65], v[98:101], v[86:89]
	v_mfma_f32_16x16x32_bf16 v[54:57], v[70:73], v[98:101], v[54:57]
	v_mfma_f32_16x16x32_bf16 v[46:49], v[62:65], v[106:109], v[46:49]
	v_mfma_f32_16x16x32_bf16 v[38:41], v[70:73], v[106:109], v[38:41]
	v_mfma_f32_16x16x32_bf16 v[30:33], v[62:65], v[180:183], v[30:33]
	v_mfma_f32_16x16x32_bf16 v[22:25], v[70:73], v[180:183], v[22:25]
	v_mfma_f32_16x16x32_bf16 v[14:17], v[62:65], v[188:191], v[14:17]
	v_mfma_f32_16x16x32_bf16 v[6:9], v[70:73], v[188:191], v[6:9]
	v_mfma_f32_16x16x32_bf16 v[86:89], v[66:69], v[102:105], v[86:89]
	v_mfma_f32_16x16x32_bf16 v[54:57], v[74:77], v[102:105], v[54:57]
	v_mfma_f32_16x16x32_bf16 v[46:49], v[66:69], v[110:113], v[46:49]
	v_mfma_f32_16x16x32_bf16 v[38:41], v[74:77], v[110:113], v[38:41]
	v_mfma_f32_16x16x32_bf16 v[30:33], v[66:69], v[184:187], v[30:33]
	v_mfma_f32_16x16x32_bf16 v[22:25], v[74:77], v[184:187], v[22:25]
	v_mfma_f32_16x16x32_bf16 v[14:17], v[66:69], v[192:195], v[14:17]
	v_mfma_f32_16x16x32_bf16 v[6:9], v[74:77], v[192:195], v[6:9]
	v_mfma_f32_16x16x32_bf16 v[58:61], v[78:81], v[98:101], v[58:61]
	v_mfma_f32_16x16x32_bf16 v[50:53], v[90:93], v[98:101], v[50:53]
	v_mfma_f32_16x16x32_bf16 v[42:45], v[78:81], v[106:109], v[42:45]
	v_mfma_f32_16x16x32_bf16 v[34:37], v[90:93], v[106:109], v[34:37]
	v_mfma_f32_16x16x32_bf16 v[26:29], v[78:81], v[180:183], v[26:29]
	v_mfma_f32_16x16x32_bf16 v[18:21], v[90:93], v[180:183], v[18:21]
	v_mfma_f32_16x16x32_bf16 v[10:13], v[78:81], v[188:191], v[10:13]
	v_mfma_f32_16x16x32_bf16 v[2:5], v[90:93], v[188:191], v[2:5]
	v_mfma_f32_16x16x32_bf16 v[58:61], v[82:85], v[102:105], v[58:61]
	v_mfma_f32_16x16x32_bf16 v[50:53], v[94:97], v[102:105], v[50:53]
	v_mfma_f32_16x16x32_bf16 v[42:45], v[82:85], v[110:113], v[42:45]
	v_mfma_f32_16x16x32_bf16 v[34:37], v[94:97], v[110:113], v[34:37]
	v_mfma_f32_16x16x32_bf16 v[26:29], v[82:85], v[184:187], v[26:29]
	v_mfma_f32_16x16x32_bf16 v[18:21], v[94:97], v[184:187], v[18:21]
	v_mfma_f32_16x16x32_bf16 v[10:13], v[82:85], v[192:195], v[10:13]
	v_mfma_f32_16x16x32_bf16 v[2:5], v[94:97], v[192:195], v[2:5]
	s_add_i32 s82, s82, 2
	s_add_u32 s2, s2, 0x100
	s_addc_u32 s3, s3, 0
	s_add_u32 s80, s80, 0x100
	s_addc_u32 s81, s81, 0
	s_cmp_gt_u32 s82, 61
	s_barrier
	s_cbranch_scc0 .LBB0_1024
	v_mov_b64_e32 v[214:215], 0x400
	s_and_b64 vcc, exec, s[16:17]
	s_cbranch_vccz .LBB0_1027
	s_barrier

.LBB0_1328:
	s_add_u32 s24, s22, 0x100
	s_addc_u32 s25, s23, 0
	s_add_i32 s57, 0, 0x10000
	s_cmpk_eq_i32 s56, 0xa8
	s_cselect_b32 s29, s3, s25
	s_cselect_b32 s28, s2, s24
	v_add_u32_e32 v146, s57, v149
	s_cselect_b32 s27, s17, s55
	s_cselect_b32 s26, s16, s54
	s_add_i32 s58, 0, 0x14000
	ds_read_b128 v[142:145], v146
	ds_read_b128 v[152:155], v146 offset:1024
	ds_read_b128 v[156:159], v146 offset:2048
	ds_read_b128 v[160:163], v146 offset:3072
	v_add_u32_e32 v146, s58, v149
	ds_read_b128 v[164:167], v146
	ds_read_b128 v[168:171], v146 offset:1024
	ds_read_b128 v[172:175], v146 offset:2048
	ds_read_b128 v[176:179], v146 offset:3072
	v_lshl_add_u64 v[146:147], s[22:23], 0, v[138:139]
	s_add_i32 m0, s41, 0xc000
	ds_read_b128 v[180:183], v151
	ds_read_b128 v[184:187], v151 offset:1024
	ds_read_b128 v[188:191], v151 offset:2048
	ds_read_b128 v[192:195], v151 offset:3072
	ds_read_b128 v[196:199], v151 offset:4096
	ds_read_b128 v[200:203], v151 offset:5120
	ds_read_b128 v[204:207], v151 offset:6144
	ds_read_b128 v[208:211], v151 offset:7168
	global_load_lds_dwordx4 v[146:147], off
	v_lshl_add_u64 v[146:147], s[22:23], 0, v[140:141]
	s_add_i32 m0, s41, 0xe000
	s_nop 0
	global_load_lds_dwordx4 v[146:147], off
	s_waitcnt vmcnt(8)
	s_waitcnt lgkmcnt(0)
	s_barrier
	s_waitcnt lgkmcnt(0)
	v_mfma_f32_16x16x32_bf16 v[126:129], v[142:145], v[180:183], v[126:129]
	v_mfma_f32_16x16x32_bf16 v[122:125], v[156:159], v[180:183], v[122:125]
	v_mfma_f32_16x16x32_bf16 v[110:113], v[142:145], v[188:191], v[110:113]
	v_mfma_f32_16x16x32_bf16 v[106:109], v[156:159], v[188:191], v[106:109]
	v_mfma_f32_16x16x32_bf16 v[94:97], v[142:145], v[196:199], v[94:97]
	v_mfma_f32_16x16x32_bf16 v[90:93], v[156:159], v[196:199], v[90:93]
	v_mfma_f32_16x16x32_bf16 v[78:81], v[142:145], v[204:207], v[78:81]
	v_mfma_f32_16x16x32_bf16 v[74:77], v[156:159], v[204:207], v[74:77]
	v_mfma_f32_16x16x32_bf16 v[126:129], v[152:155], v[184:187], v[126:129]
	v_mfma_f32_16x16x32_bf16 v[122:125], v[160:163], v[184:187], v[122:125]
	v_mfma_f32_16x16x32_bf16 v[110:113], v[152:155], v[192:195], v[110:113]
	v_mfma_f32_16x16x32_bf16 v[106:109], v[160:163], v[192:195], v[106:109]
	v_mfma_f32_16x16x32_bf16 v[94:97], v[152:155], v[200:203], v[94:97]
	v_mfma_f32_16x16x32_bf16 v[90:93], v[160:163], v[200:203], v[90:93]
	v_mfma_f32_16x16x32_bf16 v[78:81], v[152:155], v[208:211], v[78:81]
	v_mfma_f32_16x16x32_bf16 v[74:77], v[160:163], v[208:211], v[74:77]
	v_mfma_f32_16x16x32_bf16 v[118:121], v[164:167], v[180:183], v[118:121]
	v_mfma_f32_16x16x32_bf16 v[114:117], v[172:175], v[180:183], v[114:117]
	v_mfma_f32_16x16x32_bf16 v[102:105], v[164:167], v[188:191], v[102:105]
	v_mfma_f32_16x16x32_bf16 v[98:101], v[172:175], v[188:191], v[98:101]
	v_mfma_f32_16x16x32_bf16 v[86:89], v[164:167], v[196:199], v[86:89]
	v_mfma_f32_16x16x32_bf16 v[82:85], v[172:175], v[196:199], v[82:85]
	v_mfma_f32_16x16x32_bf16 v[70:73], v[164:167], v[204:207], v[70:73]
	v_mfma_f32_16x16x32_bf16 v[66:69], v[172:175], v[204:207], v[66:69]
	v_mfma_f32_16x16x32_bf16 v[118:121], v[168:171], v[184:187], v[118:121]
	v_mfma_f32_16x16x32_bf16 v[114:117], v[176:179], v[184:187], v[114:117]
	v_mfma_f32_16x16x32_bf16 v[102:105], v[168:171], v[192:195], v[102:105]
	v_mfma_f32_16x16x32_bf16 v[98:101], v[176:179], v[192:195], v[98:101]
	v_mfma_f32_16x16x32_bf16 v[86:89], v[168:171], v[200:203], v[86:89]
	v_mfma_f32_16x16x32_bf16 v[82:85], v[176:179], v[200:203], v[82:85]
	v_mfma_f32_16x16x32_bf16 v[70:73], v[168:171], v[208:211], v[70:73]
	v_mfma_f32_16x16x32_bf16 v[66:69], v[176:179], v[208:211], v[66:69]
	s_barrier
	s_add_i32 s22, s57, s40
	v_lshl_add_u64 v[146:147], s[26:27], 0, v[130:131]
	s_mov_b32 m0, s22
	ds_read_b128 v[180:183], v151 offset:16384
	ds_read_b128 v[184:187], v151 offset:17408
	ds_read_b128 v[188:191], v151 offset:18432
	ds_read_b128 v[192:195], v151 offset:19456
	ds_read_b128 v[196:199], v151 offset:20480
	ds_read_b128 v[200:203], v151 offset:21504
	ds_read_b128 v[204:207], v151 offset:22528
	ds_read_b128 v[208:211], v151 offset:23552
	global_load_lds_dwordx4 v[146:147], off
	s_add_i32 m0, s22, 0x2000
	s_add_u32 s22, s26, 0x2b0000
	v_lshl_add_u64 v[212:213], s[26:27], 0, v[132:133]
	s_addc_u32 s23, s27, 0
	s_add_i32 s57, s58, s40
	global_load_lds_dwordx4 v[212:213], off
	v_lshl_add_u64 v[216:217], s[22:23], 0, v[130:131]
	s_mov_b32 m0, s57
	v_lshl_add_u64 v[218:219], s[28:29], 0, v[134:135]
	global_load_lds_dwordx4 v[216:217], off
	v_lshl_add_u64 v[216:217], s[22:23], 0, v[132:133]
	s_add_i32 m0, s57, 0x2000
	s_nop 0
	global_load_lds_dwordx4 v[216:217], off
	v_lshl_add_u64 v[216:217], s[28:29], 0, v[136:137]
	s_mov_b32 m0, s41
	s_nop 0
	global_load_lds_dwordx4 v[216:217], off
	s_mov_b32 m0, s44
	s_nop 0
	global_load_lds_dwordx4 v[218:219], off
	s_waitcnt vmcnt(8)
	s_waitcnt lgkmcnt(0)
	s_barrier
	s_waitcnt lgkmcnt(0)
	v_mfma_f32_16x16x32_bf16 v[62:65], v[142:145], v[180:183], v[62:65]
	v_mfma_f32_16x16x32_bf16 v[58:61], v[156:159], v[180:183], v[58:61]
	v_mfma_f32_16x16x32_bf16 v[46:49], v[142:145], v[188:191], v[46:49]
	v_mfma_f32_16x16x32_bf16 v[42:45], v[156:159], v[188:191], v[42:45]
	v_mfma_f32_16x16x32_bf16 v[30:33], v[142:145], v[196:199], v[30:33]
	v_mfma_f32_16x16x32_bf16 v[26:29], v[156:159], v[196:199], v[26:29]
	v_mfma_f32_16x16x32_bf16 v[14:17], v[142:145], v[204:207], v[14:17]
	v_mfma_f32_16x16x32_bf16 v[10:13], v[156:159], v[204:207], v[10:13]
	v_mfma_f32_16x16x32_bf16 v[62:65], v[152:155], v[184:187], v[62:65]
	v_mfma_f32_16x16x32_bf16 v[58:61], v[160:163], v[184:187], v[58:61]
	v_mfma_f32_16x16x32_bf16 v[46:49], v[152:155], v[192:195], v[46:49]
	v_mfma_f32_16x16x32_bf16 v[42:45], v[160:163], v[192:195], v[42:45]
	v_mfma_f32_16x16x32_bf16 v[30:33], v[152:155], v[200:203], v[30:33]
	v_mfma_f32_16x16x32_bf16 v[26:29], v[160:163], v[200:203], v[26:29]
	v_mfma_f32_16x16x32_bf16 v[14:17], v[152:155], v[208:211], v[14:17]
	v_mfma_f32_16x16x32_bf16 v[10:13], v[160:163], v[208:211], v[10:13]
	v_mfma_f32_16x16x32_bf16 v[54:57], v[164:167], v[180:183], v[54:57]
	v_mfma_f32_16x16x32_bf16 v[50:53], v[172:175], v[180:183], v[50:53]
	v_mfma_f32_16x16x32_bf16 v[38:41], v[164:167], v[188:191], v[38:41]
	v_mfma_f32_16x16x32_bf16 v[34:37], v[172:175], v[188:191], v[34:37]
	v_mfma_f32_16x16x32_bf16 v[22:25], v[164:167], v[196:199], v[22:25]
	v_mfma_f32_16x16x32_bf16 v[18:21], v[172:175], v[196:199], v[18:21]
	v_mfma_f32_16x16x32_bf16 v[6:9], v[164:167], v[204:207], v[6:9]
	v_mfma_f32_16x16x32_bf16 v[2:5], v[172:175], v[204:207], v[2:5]
	v_mfma_f32_16x16x32_bf16 v[54:57], v[168:171], v[184:187], v[54:57]
	v_mfma_f32_16x16x32_bf16 v[50:53], v[176:179], v[184:187], v[50:53]
	v_mfma_f32_16x16x32_bf16 v[38:41], v[168:171], v[192:195], v[38:41]
	v_mfma_f32_16x16x32_bf16 v[34:37], v[176:179], v[192:195], v[34:37]
	v_mfma_f32_16x16x32_bf16 v[22:25], v[168:171], v[200:203], v[22:25]
	v_mfma_f32_16x16x32_bf16 v[18:21], v[176:179], v[200:203], v[18:21]
	v_mfma_f32_16x16x32_bf16 v[6:9], v[168:171], v[208:211], v[6:9]
	v_mfma_f32_16x16x32_bf16 v[2:5], v[176:179], v[208:211], v[2:5]
	s_barrier
	s_add_i32 s57, 0, 0x18000
	s_add_i32 s58, 0, 0x1c000
	v_add_u32_e32 v160, s57, v149
	v_add_u32_e32 v176, s58, v149
	ds_read_b128 v[142:145], v160
	ds_read_b128 v[152:155], v160 offset:1024
	ds_read_b128 v[156:159], v160 offset:2048
	ds_read_b128 v[160:163], v160 offset:3072
	ds_read_b128 v[164:167], v176
	ds_read_b128 v[168:171], v176 offset:1024
	ds_read_b128 v[172:175], v176 offset:2048
	ds_read_b128 v[176:179], v176 offset:3072
	s_add_u32 s22, s28, 0x2b0000
	s_addc_u32 s23, s29, 0
	s_mov_b32 m0, s45
	v_lshl_add_u64 v[220:221], s[22:23], 0, v[136:137]
	ds_read_b128 v[180:183], v151 offset:32768
	ds_read_b128 v[184:187], v151 offset:33792
	ds_read_b128 v[188:191], v151 offset:34816
	ds_read_b128 v[192:195], v151 offset:35840
	ds_read_b128 v[196:199], v151 offset:36864
	ds_read_b128 v[200:203], v151 offset:37888
	ds_read_b128 v[204:207], v151 offset:38912
	ds_read_b128 v[208:211], v151 offset:39936
	global_load_lds_dwordx4 v[220:221], off
	v_lshl_add_u64 v[220:221], s[22:23], 0, v[134:135]
	s_mov_b32 m0, s46
	s_nop 0
	global_load_lds_dwordx4 v[220:221], off
	s_waitcnt vmcnt(8)
	s_waitcnt lgkmcnt(0)
	s_barrier
	s_waitcnt lgkmcnt(0)
	v_mfma_f32_16x16x32_bf16 v[126:129], v[142:145], v[180:183], v[126:129]
	v_mfma_f32_16x16x32_bf16 v[122:125], v[156:159], v[180:183], v[122:125]
	v_mfma_f32_16x16x32_bf16 v[110:113], v[142:145], v[188:191], v[110:113]
	v_mfma_f32_16x16x32_bf16 v[106:109], v[156:159], v[188:191], v[106:109]
	v_mfma_f32_16x16x32_bf16 v[94:97], v[142:145], v[196:199], v[94:97]
	v_mfma_f32_16x16x32_bf16 v[90:93], v[156:159], v[196:199], v[90:93]
	v_mfma_f32_16x16x32_bf16 v[78:81], v[142:145], v[204:207], v[78:81]
	v_mfma_f32_16x16x32_bf16 v[74:77], v[156:159], v[204:207], v[74:77]
	v_mfma_f32_16x16x32_bf16 v[126:129], v[152:155], v[184:187], v[126:129]
	v_mfma_f32_16x16x32_bf16 v[122:125], v[160:163], v[184:187], v[122:125]
	v_mfma_f32_16x16x32_bf16 v[110:113], v[152:155], v[192:195], v[110:113]
	v_mfma_f32_16x16x32_bf16 v[106:109], v[160:163], v[192:195], v[106:109]
	v_mfma_f32_16x16x32_bf16 v[94:97], v[152:155], v[200:203], v[94:97]
	v_mfma_f32_16x16x32_bf16 v[90:93], v[160:163], v[200:203], v[90:93]
	v_mfma_f32_16x16x32_bf16 v[78:81], v[152:155], v[208:211], v[78:81]
	v_mfma_f32_16x16x32_bf16 v[74:77], v[160:163], v[208:211], v[74:77]
	v_mfma_f32_16x16x32_bf16 v[118:121], v[164:167], v[180:183], v[118:121]
	v_mfma_f32_16x16x32_bf16 v[114:117], v[172:175], v[180:183], v[114:117]
	v_mfma_f32_16x16x32_bf16 v[102:105], v[164:167], v[188:191], v[102:105]
	v_mfma_f32_16x16x32_bf16 v[98:101], v[172:175], v[188:191], v[98:101]
	v_mfma_f32_16x16x32_bf16 v[86:89], v[164:167], v[196:199], v[86:89]
	v_mfma_f32_16x16x32_bf16 v[82:85], v[172:175], v[196:199], v[82:85]
	v_mfma_f32_16x16x32_bf16 v[70:73], v[164:167], v[204:207], v[70:73]
	v_mfma_f32_16x16x32_bf16 v[66:69], v[172:175], v[204:207], v[66:69]
	v_mfma_f32_16x16x32_bf16 v[118:121], v[168:171], v[184:187], v[118:121]
	v_mfma_f32_16x16x32_bf16 v[114:117], v[176:179], v[184:187], v[114:117]
	v_mfma_f32_16x16x32_bf16 v[102:105], v[168:171], v[192:195], v[102:105]
	v_mfma_f32_16x16x32_bf16 v[98:101], v[176:179], v[192:195], v[98:101]
	v_mfma_f32_16x16x32_bf16 v[86:89], v[168:171], v[200:203], v[86:89]
	v_mfma_f32_16x16x32_bf16 v[82:85], v[176:179], v[200:203], v[82:85]
	v_mfma_f32_16x16x32_bf16 v[70:73], v[168:171], v[208:211], v[70:73]
	v_mfma_f32_16x16x32_bf16 v[66:69], v[176:179], v[208:211], v[66:69]
	s_barrier
	s_add_i32 s22, s57, s40
	v_lshl_add_u64 v[146:147], v[146:147], 0, s[18:19]
	s_mov_b32 m0, s22
	ds_read_b128 v[180:183], v151 offset:49152
	ds_read_b128 v[184:187], v151 offset:50176
	ds_read_b128 v[188:191], v151 offset:51200
	ds_read_b128 v[192:195], v151 offset:52224
	ds_read_b128 v[196:199], v151 offset:53248
	ds_read_b128 v[200:203], v151 offset:54272
	ds_read_b128 v[204:207], v151 offset:55296
	ds_read_b128 v[208:211], v151 offset:56320
	global_load_lds_dwordx4 v[146:147], off
	s_add_i32 m0, s22, 0x2000
	s_add_u32 s22, s26, 0x2b0080
	v_lshl_add_u64 v[146:147], v[212:213], 0, s[18:19]
	s_addc_u32 s23, s27, 0
	s_add_i32 s26, s58, s40
	global_load_lds_dwordx4 v[146:147], off
	v_lshl_add_u64 v[146:147], s[22:23], 0, v[130:131]
	s_mov_b32 m0, s26
	s_nop 0
	global_load_lds_dwordx4 v[146:147], off
	v_lshl_add_u64 v[146:147], s[22:23], 0, v[132:133]
	s_add_i32 m0, s26, 0x2000
	s_nop 0
	global_load_lds_dwordx4 v[146:147], off
	v_lshl_add_u64 v[146:147], v[216:217], 0, s[18:19]
	s_mov_b32 m0, s47
	s_nop 0
	global_load_lds_dwordx4 v[146:147], off
	v_lshl_add_u64 v[146:147], v[218:219], 0, s[18:19]
	s_mov_b32 m0, s48
	s_nop 0
	global_load_lds_dwordx4 v[146:147], off
	s_waitcnt vmcnt(8)
	s_waitcnt lgkmcnt(0)
	s_barrier
	s_waitcnt lgkmcnt(0)
	v_mfma_f32_16x16x32_bf16 v[62:65], v[142:145], v[180:183], v[62:65]
	v_mfma_f32_16x16x32_bf16 v[58:61], v[156:159], v[180:183], v[58:61]
	v_mfma_f32_16x16x32_bf16 v[46:49], v[142:145], v[188:191], v[46:49]
	v_mfma_f32_16x16x32_bf16 v[42:45], v[156:159], v[188:191], v[42:45]
	v_mfma_f32_16x16x32_bf16 v[30:33], v[142:145], v[196:199], v[30:33]
	v_mfma_f32_16x16x32_bf16 v[26:29], v[156:159], v[196:199], v[26:29]
	v_mfma_f32_16x16x32_bf16 v[14:17], v[142:145], v[204:207], v[14:17]
	v_mfma_f32_16x16x32_bf16 v[10:13], v[156:159], v[204:207], v[10:13]
	v_mfma_f32_16x16x32_bf16 v[62:65], v[152:155], v[184:187], v[62:65]
	v_mfma_f32_16x16x32_bf16 v[58:61], v[160:163], v[184:187], v[58:61]
	v_mfma_f32_16x16x32_bf16 v[46:49], v[152:155], v[192:195], v[46:49]
	v_mfma_f32_16x16x32_bf16 v[42:45], v[160:163], v[192:195], v[42:45]
	v_mfma_f32_16x16x32_bf16 v[30:33], v[152:155], v[200:203], v[30:33]
	v_mfma_f32_16x16x32_bf16 v[26:29], v[160:163], v[200:203], v[26:29]
	v_mfma_f32_16x16x32_bf16 v[14:17], v[152:155], v[208:211], v[14:17]
	v_mfma_f32_16x16x32_bf16 v[10:13], v[160:163], v[208:211], v[10:13]
	v_mfma_f32_16x16x32_bf16 v[54:57], v[164:167], v[180:183], v[54:57]
	v_mfma_f32_16x16x32_bf16 v[50:53], v[172:175], v[180:183], v[50:53]
	v_mfma_f32_16x16x32_bf16 v[38:41], v[164:167], v[188:191], v[38:41]
	v_mfma_f32_16x16x32_bf16 v[34:37], v[172:175], v[188:191], v[34:37]
	v_mfma_f32_16x16x32_bf16 v[22:25], v[164:167], v[196:199], v[22:25]
	v_mfma_f32_16x16x32_bf16 v[18:21], v[172:175], v[196:199], v[18:21]
	v_mfma_f32_16x16x32_bf16 v[6:9], v[164:167], v[204:207], v[6:9]
	v_mfma_f32_16x16x32_bf16 v[2:5], v[172:175], v[204:207], v[2:5]
	v_mfma_f32_16x16x32_bf16 v[54:57], v[168:171], v[184:187], v[54:57]
	v_mfma_f32_16x16x32_bf16 v[50:53], v[176:179], v[184:187], v[50:53]
	v_mfma_f32_16x16x32_bf16 v[38:41], v[168:171], v[192:195], v[38:41]
	v_mfma_f32_16x16x32_bf16 v[34:37], v[176:179], v[192:195], v[34:37]
	v_mfma_f32_16x16x32_bf16 v[22:25], v[168:171], v[200:203], v[22:25]
	v_mfma_f32_16x16x32_bf16 v[18:21], v[176:179], v[200:203], v[18:21]
	v_mfma_f32_16x16x32_bf16 v[6:9], v[168:171], v[208:211], v[6:9]
	v_mfma_f32_16x16x32_bf16 v[2:5], v[176:179], v[208:211], v[2:5]
	s_add_i32 s56, s56, 2
	s_add_u32 s54, s54, 0x100
	s_addc_u32 s55, s55, 0
	s_cmpk_gt_u32 s56, 0xa9
	s_mov_b64 s[22:23], s[24:25]
	s_barrier
	s_cbranch_scc0 .LBB0_1328
	s_and_b64 vcc, exec, s[12:13]
	s_cbranch_vccz .LBB0_1331
	s_barrier

.LBB0_1354:
	s_add_u32 s24, s22, 0x100
	s_addc_u32 s25, s23, 0
	s_add_i32 s60, 0, 0x10000
	s_cmpk_eq_i32 s59, 0xa8
	s_cselect_b32 s29, s3, s25
	s_cselect_b32 s28, s2, s24
	v_add_u32_e32 v149, s60, v194
	s_cselect_b32 s27, s13, s58
	s_cselect_b32 s26, s12, s57
	s_add_i32 s61, 0, 0x14000
	ds_read_b128 v[132:135], v149
	ds_read_b128 v[150:153], v149 offset:1024
	ds_read_b128 v[154:157], v149 offset:2048
	ds_read_b128 v[158:161], v149 offset:3072
	v_add_u32_e32 v149, s61, v194
	ds_read_b128 v[162:165], v149
	ds_read_b128 v[166:169], v149 offset:1024
	ds_read_b128 v[170:173], v149 offset:2048
	ds_read_b128 v[174:177], v149 offset:3072
	v_lshl_add_u64 v[190:191], s[22:23], 0, v[144:145]
	s_add_i32 m0, s48, 0xc000
	ds_read_b128 v[178:181], v196
	ds_read_b128 v[182:185], v196 offset:1024
	ds_read_b128 v[186:189], v196 offset:2048
	ds_read_b128 v[198:201], v196 offset:3072
	ds_read_b128 v[202:205], v196 offset:4096
	ds_read_b128 v[206:209], v196 offset:5120
	ds_read_b128 v[210:213], v196 offset:6144
	ds_read_b128 v[216:219], v196 offset:7168
	global_load_lds_dwordx4 v[190:191], off
	v_lshl_add_u64 v[190:191], s[22:23], 0, v[146:147]
	s_add_i32 m0, s48, 0xe000
	s_nop 0
	global_load_lds_dwordx4 v[190:191], off
	s_waitcnt vmcnt(8)
	s_waitcnt lgkmcnt(0)
	s_barrier
	s_waitcnt lgkmcnt(0)
	v_mfma_f32_16x16x32_bf16 v[126:129], v[132:135], v[178:181], v[126:129]
	v_mfma_f32_16x16x32_bf16 v[122:125], v[154:157], v[178:181], v[122:125]
	v_mfma_f32_16x16x32_bf16 v[110:113], v[132:135], v[186:189], v[110:113]
	v_mfma_f32_16x16x32_bf16 v[106:109], v[154:157], v[186:189], v[106:109]
	v_mfma_f32_16x16x32_bf16 v[94:97], v[132:135], v[202:205], v[94:97]
	v_mfma_f32_16x16x32_bf16 v[90:93], v[154:157], v[202:205], v[90:93]
	v_mfma_f32_16x16x32_bf16 v[78:81], v[132:135], v[210:213], v[78:81]
	v_mfma_f32_16x16x32_bf16 v[74:77], v[154:157], v[210:213], v[74:77]
	v_mfma_f32_16x16x32_bf16 v[126:129], v[150:153], v[182:185], v[126:129]
	v_mfma_f32_16x16x32_bf16 v[122:125], v[158:161], v[182:185], v[122:125]
	v_mfma_f32_16x16x32_bf16 v[110:113], v[150:153], v[198:201], v[110:113]
	v_mfma_f32_16x16x32_bf16 v[106:109], v[158:161], v[198:201], v[106:109]
	v_mfma_f32_16x16x32_bf16 v[94:97], v[150:153], v[206:209], v[94:97]
	v_mfma_f32_16x16x32_bf16 v[90:93], v[158:161], v[206:209], v[90:93]
	v_mfma_f32_16x16x32_bf16 v[78:81], v[150:153], v[216:219], v[78:81]
	v_mfma_f32_16x16x32_bf16 v[74:77], v[158:161], v[216:219], v[74:77]
	v_mfma_f32_16x16x32_bf16 v[118:121], v[162:165], v[178:181], v[118:121]
	v_mfma_f32_16x16x32_bf16 v[114:117], v[170:173], v[178:181], v[114:117]
	v_mfma_f32_16x16x32_bf16 v[102:105], v[162:165], v[186:189], v[102:105]
	v_mfma_f32_16x16x32_bf16 v[98:101], v[170:173], v[186:189], v[98:101]
	v_mfma_f32_16x16x32_bf16 v[86:89], v[162:165], v[202:205], v[86:89]
	v_mfma_f32_16x16x32_bf16 v[82:85], v[170:173], v[202:205], v[82:85]
	v_mfma_f32_16x16x32_bf16 v[70:73], v[162:165], v[210:213], v[70:73]
	v_mfma_f32_16x16x32_bf16 v[66:69], v[170:173], v[210:213], v[66:69]
	v_mfma_f32_16x16x32_bf16 v[118:121], v[166:169], v[182:185], v[118:121]
	v_mfma_f32_16x16x32_bf16 v[114:117], v[174:177], v[182:185], v[114:117]
	v_mfma_f32_16x16x32_bf16 v[102:105], v[166:169], v[198:201], v[102:105]
	v_mfma_f32_16x16x32_bf16 v[98:101], v[174:177], v[198:201], v[98:101]
	v_mfma_f32_16x16x32_bf16 v[86:89], v[166:169], v[206:209], v[86:89]
	v_mfma_f32_16x16x32_bf16 v[82:85], v[174:177], v[206:209], v[82:85]
	v_mfma_f32_16x16x32_bf16 v[70:73], v[166:169], v[216:219], v[70:73]
	v_mfma_f32_16x16x32_bf16 v[66:69], v[174:177], v[216:219], v[66:69]
	s_barrier
	s_add_i32 s22, s60, s30
	v_lshl_add_u64 v[190:191], s[26:27], 0, v[140:141]
	s_mov_b32 m0, s22
	ds_read_b128 v[178:181], v196 offset:16384
	ds_read_b128 v[182:185], v196 offset:17408
	ds_read_b128 v[186:189], v196 offset:18432
	ds_read_b128 v[198:201], v196 offset:19456
	ds_read_b128 v[202:205], v196 offset:20480
	ds_read_b128 v[206:209], v196 offset:21504
	ds_read_b128 v[210:213], v196 offset:22528
	ds_read_b128 v[216:219], v196 offset:23552
	global_load_lds_dwordx4 v[190:191], off
	s_add_i32 m0, s22, 0x2000
	s_add_u32 s22, s26, 0x2b0000
	v_lshl_add_u64 v[220:221], s[26:27], 0, v[136:137]
	s_addc_u32 s23, s27, 0
	s_add_i32 s60, s61, s30
	global_load_lds_dwordx4 v[220:221], off
	v_lshl_add_u64 v[222:223], s[22:23], 0, v[140:141]
	s_mov_b32 m0, s60
	v_lshl_add_u64 v[224:225], s[28:29], 0, v[138:139]
	global_load_lds_dwordx4 v[222:223], off
	v_lshl_add_u64 v[222:223], s[22:23], 0, v[136:137]
	s_add_i32 m0, s60, 0x2000
	s_nop 0
	global_load_lds_dwordx4 v[222:223], off
	v_lshl_add_u64 v[222:223], s[28:29], 0, v[142:143]
	s_mov_b32 m0, s48
	s_nop 0
	global_load_lds_dwordx4 v[222:223], off
	s_mov_b32 m0, s49
	s_nop 0
	global_load_lds_dwordx4 v[224:225], off
	s_waitcnt vmcnt(8)
	s_waitcnt lgkmcnt(0)
	s_barrier
	s_waitcnt lgkmcnt(0)
	v_mfma_f32_16x16x32_bf16 v[62:65], v[132:135], v[178:181], v[62:65]
	v_mfma_f32_16x16x32_bf16 v[58:61], v[154:157], v[178:181], v[58:61]
	v_mfma_f32_16x16x32_bf16 v[46:49], v[132:135], v[186:189], v[46:49]
	v_mfma_f32_16x16x32_bf16 v[42:45], v[154:157], v[186:189], v[42:45]
	v_mfma_f32_16x16x32_bf16 v[30:33], v[132:135], v[202:205], v[30:33]
	v_mfma_f32_16x16x32_bf16 v[26:29], v[154:157], v[202:205], v[26:29]
	v_mfma_f32_16x16x32_bf16 v[14:17], v[132:135], v[210:213], v[14:17]
	v_mfma_f32_16x16x32_bf16 v[10:13], v[154:157], v[210:213], v[10:13]
	v_mfma_f32_16x16x32_bf16 v[62:65], v[150:153], v[182:185], v[62:65]
	v_mfma_f32_16x16x32_bf16 v[58:61], v[158:161], v[182:185], v[58:61]
	v_mfma_f32_16x16x32_bf16 v[46:49], v[150:153], v[198:201], v[46:49]
	v_mfma_f32_16x16x32_bf16 v[42:45], v[158:161], v[198:201], v[42:45]
	v_mfma_f32_16x16x32_bf16 v[30:33], v[150:153], v[206:209], v[30:33]
	v_mfma_f32_16x16x32_bf16 v[26:29], v[158:161], v[206:209], v[26:29]
	v_mfma_f32_16x16x32_bf16 v[14:17], v[150:153], v[216:219], v[14:17]
	v_mfma_f32_16x16x32_bf16 v[10:13], v[158:161], v[216:219], v[10:13]
	v_mfma_f32_16x16x32_bf16 v[54:57], v[162:165], v[178:181], v[54:57]
	v_mfma_f32_16x16x32_bf16 v[50:53], v[170:173], v[178:181], v[50:53]
	v_mfma_f32_16x16x32_bf16 v[38:41], v[162:165], v[186:189], v[38:41]
	v_mfma_f32_16x16x32_bf16 v[34:37], v[170:173], v[186:189], v[34:37]
	v_mfma_f32_16x16x32_bf16 v[22:25], v[162:165], v[202:205], v[22:25]
	v_mfma_f32_16x16x32_bf16 v[18:21], v[170:173], v[202:205], v[18:21]
	v_mfma_f32_16x16x32_bf16 v[6:9], v[162:165], v[210:213], v[6:9]
	v_mfma_f32_16x16x32_bf16 v[2:5], v[170:173], v[210:213], v[2:5]
	v_mfma_f32_16x16x32_bf16 v[54:57], v[166:169], v[182:185], v[54:57]
	v_mfma_f32_16x16x32_bf16 v[50:53], v[174:177], v[182:185], v[50:53]
	v_mfma_f32_16x16x32_bf16 v[38:41], v[166:169], v[198:201], v[38:41]
	v_mfma_f32_16x16x32_bf16 v[34:37], v[174:177], v[198:201], v[34:37]
	v_mfma_f32_16x16x32_bf16 v[22:25], v[166:169], v[206:209], v[22:25]
	v_mfma_f32_16x16x32_bf16 v[18:21], v[174:177], v[206:209], v[18:21]
	v_mfma_f32_16x16x32_bf16 v[6:9], v[166:169], v[216:219], v[6:9]
	v_mfma_f32_16x16x32_bf16 v[2:5], v[174:177], v[216:219], v[2:5]
	s_barrier
	s_add_i32 s60, 0, 0x18000
	v_add_u32_e32 v149, s60, v194
	s_add_i32 s61, 0, 0x1c000
	ds_read_b128 v[132:135], v149
	ds_read_b128 v[150:153], v149 offset:1024
	ds_read_b128 v[154:157], v149 offset:2048
	ds_read_b128 v[158:161], v149 offset:3072
	v_add_u32_e32 v149, s61, v194
	ds_read_b128 v[162:165], v149
	ds_read_b128 v[166:169], v149 offset:1024
	ds_read_b128 v[170:173], v149 offset:2048
	ds_read_b128 v[174:177], v149 offset:3072
	s_add_u32 s22, s28, 0x2b0000
	s_addc_u32 s23, s29, 0
	s_mov_b32 m0, s50
	v_lshl_add_u64 v[226:227], s[22:23], 0, v[142:143]
	ds_read_b128 v[178:181], v196 offset:32768
	ds_read_b128 v[182:185], v196 offset:33792
	ds_read_b128 v[186:189], v196 offset:34816
	ds_read_b128 v[198:201], v196 offset:35840
	ds_read_b128 v[202:205], v196 offset:36864
	ds_read_b128 v[206:209], v196 offset:37888
	ds_read_b128 v[210:213], v196 offset:38912
	ds_read_b128 v[216:219], v196 offset:39936
	global_load_lds_dwordx4 v[226:227], off
	v_lshl_add_u64 v[226:227], s[22:23], 0, v[138:139]
	s_mov_b32 m0, s51
	s_nop 0
	global_load_lds_dwordx4 v[226:227], off
	s_waitcnt vmcnt(8)
	s_waitcnt lgkmcnt(0)
	s_barrier
	s_waitcnt lgkmcnt(0)
	v_mfma_f32_16x16x32_bf16 v[126:129], v[132:135], v[178:181], v[126:129]
	v_mfma_f32_16x16x32_bf16 v[122:125], v[154:157], v[178:181], v[122:125]
	v_mfma_f32_16x16x32_bf16 v[110:113], v[132:135], v[186:189], v[110:113]
	v_mfma_f32_16x16x32_bf16 v[106:109], v[154:157], v[186:189], v[106:109]
	v_mfma_f32_16x16x32_bf16 v[94:97], v[132:135], v[202:205], v[94:97]
	v_mfma_f32_16x16x32_bf16 v[90:93], v[154:157], v[202:205], v[90:93]
	v_mfma_f32_16x16x32_bf16 v[78:81], v[132:135], v[210:213], v[78:81]
	v_mfma_f32_16x16x32_bf16 v[74:77], v[154:157], v[210:213], v[74:77]
	v_mfma_f32_16x16x32_bf16 v[126:129], v[150:153], v[182:185], v[126:129]
	v_mfma_f32_16x16x32_bf16 v[122:125], v[158:161], v[182:185], v[122:125]
	v_mfma_f32_16x16x32_bf16 v[110:113], v[150:153], v[198:201], v[110:113]
	v_mfma_f32_16x16x32_bf16 v[106:109], v[158:161], v[198:201], v[106:109]
	v_mfma_f32_16x16x32_bf16 v[94:97], v[150:153], v[206:209], v[94:97]
	v_mfma_f32_16x16x32_bf16 v[90:93], v[158:161], v[206:209], v[90:93]
	v_mfma_f32_16x16x32_bf16 v[78:81], v[150:153], v[216:219], v[78:81]
	v_mfma_f32_16x16x32_bf16 v[74:77], v[158:161], v[216:219], v[74:77]
	v_mfma_f32_16x16x32_bf16 v[118:121], v[162:165], v[178:181], v[118:121]
	v_mfma_f32_16x16x32_bf16 v[114:117], v[170:173], v[178:181], v[114:117]
	v_mfma_f32_16x16x32_bf16 v[102:105], v[162:165], v[186:189], v[102:105]
	v_mfma_f32_16x16x32_bf16 v[98:101], v[170:173], v[186:189], v[98:101]
	v_mfma_f32_16x16x32_bf16 v[86:89], v[162:165], v[202:205], v[86:89]
	v_mfma_f32_16x16x32_bf16 v[82:85], v[170:173], v[202:205], v[82:85]
	v_mfma_f32_16x16x32_bf16 v[70:73], v[162:165], v[210:213], v[70:73]
	v_mfma_f32_16x16x32_bf16 v[66:69], v[170:173], v[210:213], v[66:69]
	v_mfma_f32_16x16x32_bf16 v[118:121], v[166:169], v[182:185], v[118:121]
	v_mfma_f32_16x16x32_bf16 v[114:117], v[174:177], v[182:185], v[114:117]
	v_mfma_f32_16x16x32_bf16 v[102:105], v[166:169], v[198:201], v[102:105]
	v_mfma_f32_16x16x32_bf16 v[98:101], v[174:177], v[198:201], v[98:101]
	v_mfma_f32_16x16x32_bf16 v[86:89], v[166:169], v[206:209], v[86:89]
	v_mfma_f32_16x16x32_bf16 v[82:85], v[174:177], v[206:209], v[82:85]
	v_mfma_f32_16x16x32_bf16 v[70:73], v[166:169], v[216:219], v[70:73]
	v_mfma_f32_16x16x32_bf16 v[66:69], v[174:177], v[216:219], v[66:69]
	s_barrier
	s_add_i32 s22, s60, s30
	v_lshl_add_u64 v[190:191], v[190:191], 0, s[18:19]
	s_mov_b32 m0, s22
	ds_read_b128 v[178:181], v196 offset:49152
	ds_read_b128 v[182:185], v196 offset:50176
	ds_read_b128 v[186:189], v196 offset:51200
	ds_read_b128 v[198:201], v196 offset:52224
	ds_read_b128 v[202:205], v196 offset:53248
	ds_read_b128 v[206:209], v196 offset:54272
	ds_read_b128 v[210:213], v196 offset:55296
	ds_read_b128 v[216:219], v196 offset:56320
	global_load_lds_dwordx4 v[190:191], off
	s_add_i32 m0, s22, 0x2000
	s_add_u32 s22, s26, 0x2b0080
	v_lshl_add_u64 v[190:191], v[220:221], 0, s[18:19]
	s_addc_u32 s23, s27, 0
	s_add_i32 s26, s61, s30
	global_load_lds_dwordx4 v[190:191], off
	v_lshl_add_u64 v[190:191], s[22:23], 0, v[140:141]
	s_mov_b32 m0, s26
	s_nop 0
	global_load_lds_dwordx4 v[190:191], off
	v_lshl_add_u64 v[190:191], s[22:23], 0, v[136:137]
	s_add_i32 m0, s26, 0x2000
	s_nop 0
	global_load_lds_dwordx4 v[190:191], off
	v_lshl_add_u64 v[190:191], v[222:223], 0, s[18:19]
	s_mov_b32 m0, s52
	s_nop 0
	global_load_lds_dwordx4 v[190:191], off
	v_lshl_add_u64 v[190:191], v[224:225], 0, s[18:19]
	s_mov_b32 m0, s53
	s_nop 0
	global_load_lds_dwordx4 v[190:191], off
	s_waitcnt vmcnt(8)
	s_waitcnt lgkmcnt(0)
	s_barrier
	s_waitcnt lgkmcnt(0)
	v_mfma_f32_16x16x32_bf16 v[62:65], v[132:135], v[178:181], v[62:65]
	v_mfma_f32_16x16x32_bf16 v[58:61], v[154:157], v[178:181], v[58:61]
	v_mfma_f32_16x16x32_bf16 v[46:49], v[132:135], v[186:189], v[46:49]
	v_mfma_f32_16x16x32_bf16 v[42:45], v[154:157], v[186:189], v[42:45]
	v_mfma_f32_16x16x32_bf16 v[30:33], v[132:135], v[202:205], v[30:33]
	v_mfma_f32_16x16x32_bf16 v[26:29], v[154:157], v[202:205], v[26:29]
	v_mfma_f32_16x16x32_bf16 v[14:17], v[132:135], v[210:213], v[14:17]
	v_mfma_f32_16x16x32_bf16 v[10:13], v[154:157], v[210:213], v[10:13]
	v_mfma_f32_16x16x32_bf16 v[62:65], v[150:153], v[182:185], v[62:65]
	v_mfma_f32_16x16x32_bf16 v[58:61], v[158:161], v[182:185], v[58:61]
	v_mfma_f32_16x16x32_bf16 v[46:49], v[150:153], v[198:201], v[46:49]
	v_mfma_f32_16x16x32_bf16 v[42:45], v[158:161], v[198:201], v[42:45]
	v_mfma_f32_16x16x32_bf16 v[30:33], v[150:153], v[206:209], v[30:33]
	v_mfma_f32_16x16x32_bf16 v[26:29], v[158:161], v[206:209], v[26:29]
	v_mfma_f32_16x16x32_bf16 v[14:17], v[150:153], v[216:219], v[14:17]
	v_mfma_f32_16x16x32_bf16 v[10:13], v[158:161], v[216:219], v[10:13]
	v_mfma_f32_16x16x32_bf16 v[54:57], v[162:165], v[178:181], v[54:57]
	v_mfma_f32_16x16x32_bf16 v[50:53], v[170:173], v[178:181], v[50:53]
	v_mfma_f32_16x16x32_bf16 v[38:41], v[162:165], v[186:189], v[38:41]
	v_mfma_f32_16x16x32_bf16 v[34:37], v[170:173], v[186:189], v[34:37]
	v_mfma_f32_16x16x32_bf16 v[22:25], v[162:165], v[202:205], v[22:25]
	v_mfma_f32_16x16x32_bf16 v[18:21], v[170:173], v[202:205], v[18:21]
	v_mfma_f32_16x16x32_bf16 v[6:9], v[162:165], v[210:213], v[6:9]
	v_mfma_f32_16x16x32_bf16 v[2:5], v[170:173], v[210:213], v[2:5]
	v_mfma_f32_16x16x32_bf16 v[54:57], v[166:169], v[182:185], v[54:57]
	v_mfma_f32_16x16x32_bf16 v[50:53], v[174:177], v[182:185], v[50:53]
	v_mfma_f32_16x16x32_bf16 v[38:41], v[166:169], v[198:201], v[38:41]
	v_mfma_f32_16x16x32_bf16 v[34:37], v[174:177], v[198:201], v[34:37]
	v_mfma_f32_16x16x32_bf16 v[22:25], v[166:169], v[206:209], v[22:25]
	v_mfma_f32_16x16x32_bf16 v[18:21], v[174:177], v[206:209], v[18:21]
	v_mfma_f32_16x16x32_bf16 v[6:9], v[166:169], v[216:219], v[6:9]
	v_mfma_f32_16x16x32_bf16 v[2:5], v[174:177], v[216:219], v[2:5]
	s_add_i32 s59, s59, 2
	s_add_u32 s57, s57, 0x100
	s_addc_u32 s58, s58, 0
	s_cmpk_gt_u32 s59, 0xa9
	s_mov_b64 s[22:23], s[24:25]
	s_barrier
	s_cbranch_scc0 .LBB0_1354
	s_and_b64 vcc, exec, s[46:47]
	s_cbranch_vccz .LBB0_1357
	s_barrier

.LBB0_1405:
	s_add_u32 s22, s16, 0x100
	s_addc_u32 s23, s17, 0
	s_add_i32 s54, 0, 0x10000
	s_cmpk_eq_i32 s53, 0xa8
	s_cselect_b32 s27, s3, s23
	s_cselect_b32 s26, s2, s22
	v_add_u32_e32 v148, s54, v152
	s_cselect_b32 s25, s13, s52
	s_cselect_b32 s24, s12, s51
	s_add_i32 s55, 0, 0x14000
	ds_read_b128 v[144:147], v148
	ds_read_b128 v[156:159], v148 offset:1024
	ds_read_b128 v[160:163], v148 offset:2048
	ds_read_b128 v[164:167], v148 offset:3072
	v_add_u32_e32 v148, s55, v152
	ds_read_b128 v[168:171], v148
	ds_read_b128 v[172:175], v148 offset:1024
	ds_read_b128 v[176:179], v148 offset:2048
	ds_read_b128 v[180:183], v148 offset:3072
	v_lshl_add_u64 v[148:149], s[16:17], 0, v[140:141]
	s_add_i32 m0, s29, 0xc000
	ds_read_b128 v[184:187], v154
	ds_read_b128 v[188:191], v154 offset:1024
	ds_read_b128 v[192:195], v154 offset:2048
	ds_read_b128 v[196:199], v154 offset:3072
	ds_read_b128 v[200:203], v154 offset:4096
	ds_read_b128 v[204:207], v154 offset:5120
	ds_read_b128 v[208:211], v154 offset:6144
	ds_read_b128 v[216:219], v154 offset:7168
	global_load_lds_dwordx4 v[148:149], off
	v_lshl_add_u64 v[148:149], s[16:17], 0, v[142:143]
	s_add_i32 m0, s29, 0xe000
	s_nop 0
	global_load_lds_dwordx4 v[148:149], off
	s_waitcnt vmcnt(8)
	s_waitcnt lgkmcnt(0)
	s_barrier
	s_waitcnt lgkmcnt(0)
	v_mfma_f32_16x16x32_bf16 v[126:129], v[144:147], v[184:187], v[126:129]
	v_mfma_f32_16x16x32_bf16 v[122:125], v[160:163], v[184:187], v[122:125]
	v_mfma_f32_16x16x32_bf16 v[110:113], v[144:147], v[192:195], v[110:113]
	v_mfma_f32_16x16x32_bf16 v[106:109], v[160:163], v[192:195], v[106:109]
	v_mfma_f32_16x16x32_bf16 v[94:97], v[144:147], v[200:203], v[94:97]
	v_mfma_f32_16x16x32_bf16 v[90:93], v[160:163], v[200:203], v[90:93]
	v_mfma_f32_16x16x32_bf16 v[78:81], v[144:147], v[208:211], v[78:81]
	v_mfma_f32_16x16x32_bf16 v[74:77], v[160:163], v[208:211], v[74:77]
	v_mfma_f32_16x16x32_bf16 v[126:129], v[156:159], v[188:191], v[126:129]
	v_mfma_f32_16x16x32_bf16 v[122:125], v[164:167], v[188:191], v[122:125]
	v_mfma_f32_16x16x32_bf16 v[110:113], v[156:159], v[196:199], v[110:113]
	v_mfma_f32_16x16x32_bf16 v[106:109], v[164:167], v[196:199], v[106:109]
	v_mfma_f32_16x16x32_bf16 v[94:97], v[156:159], v[204:207], v[94:97]
	v_mfma_f32_16x16x32_bf16 v[90:93], v[164:167], v[204:207], v[90:93]
	v_mfma_f32_16x16x32_bf16 v[78:81], v[156:159], v[216:219], v[78:81]
	v_mfma_f32_16x16x32_bf16 v[74:77], v[164:167], v[216:219], v[74:77]
	v_mfma_f32_16x16x32_bf16 v[118:121], v[168:171], v[184:187], v[118:121]
	v_mfma_f32_16x16x32_bf16 v[114:117], v[176:179], v[184:187], v[114:117]
	v_mfma_f32_16x16x32_bf16 v[102:105], v[168:171], v[192:195], v[102:105]
	v_mfma_f32_16x16x32_bf16 v[98:101], v[176:179], v[192:195], v[98:101]
	v_mfma_f32_16x16x32_bf16 v[86:89], v[168:171], v[200:203], v[86:89]
	v_mfma_f32_16x16x32_bf16 v[82:85], v[176:179], v[200:203], v[82:85]
	v_mfma_f32_16x16x32_bf16 v[70:73], v[168:171], v[208:211], v[70:73]
	v_mfma_f32_16x16x32_bf16 v[66:69], v[176:179], v[208:211], v[66:69]
	v_mfma_f32_16x16x32_bf16 v[118:121], v[172:175], v[188:191], v[118:121]
	v_mfma_f32_16x16x32_bf16 v[114:117], v[180:183], v[188:191], v[114:117]
	v_mfma_f32_16x16x32_bf16 v[102:105], v[172:175], v[196:199], v[102:105]
	v_mfma_f32_16x16x32_bf16 v[98:101], v[180:183], v[196:199], v[98:101]
	v_mfma_f32_16x16x32_bf16 v[86:89], v[172:175], v[204:207], v[86:89]
	v_mfma_f32_16x16x32_bf16 v[82:85], v[180:183], v[204:207], v[82:85]
	v_mfma_f32_16x16x32_bf16 v[70:73], v[172:175], v[216:219], v[70:73]
	v_mfma_f32_16x16x32_bf16 v[66:69], v[180:183], v[216:219], v[66:69]
	s_barrier
	s_add_i32 s16, s54, s28
	v_lshl_add_u64 v[148:149], s[24:25], 0, v[130:131]
	s_mov_b32 m0, s16
	ds_read_b128 v[184:187], v154 offset:16384
	ds_read_b128 v[188:191], v154 offset:17408
	ds_read_b128 v[192:195], v154 offset:18432
	ds_read_b128 v[196:199], v154 offset:19456
	ds_read_b128 v[200:203], v154 offset:20480
	ds_read_b128 v[204:207], v154 offset:21504
	ds_read_b128 v[208:211], v154 offset:22528
	ds_read_b128 v[216:219], v154 offset:23552
	global_load_lds_dwordx4 v[148:149], off
	s_add_i32 m0, s16, 0x2000
	s_add_u32 s16, s24, 0x2b0000
	v_lshl_add_u64 v[212:213], s[24:25], 0, v[132:133]
	s_addc_u32 s17, s25, 0
	s_add_i32 s54, s55, s28
	global_load_lds_dwordx4 v[212:213], off
	v_lshl_add_u64 v[220:221], s[16:17], 0, v[130:131]
	s_mov_b32 m0, s54
	v_lshl_add_u64 v[222:223], s[26:27], 0, v[134:135]
	global_load_lds_dwordx4 v[220:221], off
	v_lshl_add_u64 v[220:221], s[16:17], 0, v[132:133]
	s_add_i32 m0, s54, 0x2000
	s_nop 0
	global_load_lds_dwordx4 v[220:221], off
	v_lshl_add_u64 v[220:221], s[26:27], 0, v[136:137]
	s_mov_b32 m0, s29
	s_nop 0
	global_load_lds_dwordx4 v[220:221], off
	s_mov_b32 m0, s30
	s_nop 0
	global_load_lds_dwordx4 v[222:223], off
	s_waitcnt vmcnt(8)
	s_waitcnt lgkmcnt(0)
	s_barrier
	s_waitcnt lgkmcnt(0)
	v_mfma_f32_16x16x32_bf16 v[62:65], v[144:147], v[184:187], v[62:65]
	v_mfma_f32_16x16x32_bf16 v[58:61], v[160:163], v[184:187], v[58:61]
	v_mfma_f32_16x16x32_bf16 v[46:49], v[144:147], v[192:195], v[46:49]
	v_mfma_f32_16x16x32_bf16 v[42:45], v[160:163], v[192:195], v[42:45]
	v_mfma_f32_16x16x32_bf16 v[30:33], v[144:147], v[200:203], v[30:33]
	v_mfma_f32_16x16x32_bf16 v[26:29], v[160:163], v[200:203], v[26:29]
	v_mfma_f32_16x16x32_bf16 v[14:17], v[144:147], v[208:211], v[14:17]
	v_mfma_f32_16x16x32_bf16 v[10:13], v[160:163], v[208:211], v[10:13]
	v_mfma_f32_16x16x32_bf16 v[62:65], v[156:159], v[188:191], v[62:65]
	v_mfma_f32_16x16x32_bf16 v[58:61], v[164:167], v[188:191], v[58:61]
	v_mfma_f32_16x16x32_bf16 v[46:49], v[156:159], v[196:199], v[46:49]
	v_mfma_f32_16x16x32_bf16 v[42:45], v[164:167], v[196:199], v[42:45]
	v_mfma_f32_16x16x32_bf16 v[30:33], v[156:159], v[204:207], v[30:33]
	v_mfma_f32_16x16x32_bf16 v[26:29], v[164:167], v[204:207], v[26:29]
	v_mfma_f32_16x16x32_bf16 v[14:17], v[156:159], v[216:219], v[14:17]
	v_mfma_f32_16x16x32_bf16 v[10:13], v[164:167], v[216:219], v[10:13]
	v_mfma_f32_16x16x32_bf16 v[54:57], v[168:171], v[184:187], v[54:57]
	v_mfma_f32_16x16x32_bf16 v[50:53], v[176:179], v[184:187], v[50:53]
	v_mfma_f32_16x16x32_bf16 v[38:41], v[168:171], v[192:195], v[38:41]
	v_mfma_f32_16x16x32_bf16 v[34:37], v[176:179], v[192:195], v[34:37]
	v_mfma_f32_16x16x32_bf16 v[22:25], v[168:171], v[200:203], v[22:25]
	v_mfma_f32_16x16x32_bf16 v[18:21], v[176:179], v[200:203], v[18:21]
	v_mfma_f32_16x16x32_bf16 v[6:9], v[168:171], v[208:211], v[6:9]
	v_mfma_f32_16x16x32_bf16 v[2:5], v[176:179], v[208:211], v[2:5]
	v_mfma_f32_16x16x32_bf16 v[54:57], v[172:175], v[188:191], v[54:57]
	v_mfma_f32_16x16x32_bf16 v[50:53], v[180:183], v[188:191], v[50:53]
	v_mfma_f32_16x16x32_bf16 v[38:41], v[172:175], v[196:199], v[38:41]
	v_mfma_f32_16x16x32_bf16 v[34:37], v[180:183], v[196:199], v[34:37]
	v_mfma_f32_16x16x32_bf16 v[22:25], v[172:175], v[204:207], v[22:25]
	v_mfma_f32_16x16x32_bf16 v[18:21], v[180:183], v[204:207], v[18:21]
	v_mfma_f32_16x16x32_bf16 v[6:9], v[172:175], v[216:219], v[6:9]
	v_mfma_f32_16x16x32_bf16 v[2:5], v[180:183], v[216:219], v[2:5]
	s_barrier
	s_add_i32 s54, 0, 0x18000
	v_add_u32_e32 v155, s54, v152
	s_add_i32 s55, 0, 0x1c000
	ds_read_b128 v[144:147], v155
	ds_read_b128 v[156:159], v155 offset:1024
	ds_read_b128 v[160:163], v155 offset:2048
	ds_read_b128 v[164:167], v155 offset:3072
	v_add_u32_e32 v155, s55, v152
	ds_read_b128 v[168:171], v155
	ds_read_b128 v[172:175], v155 offset:1024
	ds_read_b128 v[176:179], v155 offset:2048
	ds_read_b128 v[180:183], v155 offset:3072
	s_add_u32 s16, s26, 0x2b0000
	s_addc_u32 s17, s27, 0
	s_mov_b32 m0, s40
	v_lshl_add_u64 v[224:225], s[16:17], 0, v[136:137]
	ds_read_b128 v[184:187], v154 offset:32768
	ds_read_b128 v[188:191], v154 offset:33792
	ds_read_b128 v[192:195], v154 offset:34816
	ds_read_b128 v[196:199], v154 offset:35840
	ds_read_b128 v[200:203], v154 offset:36864
	ds_read_b128 v[204:207], v154 offset:37888
	ds_read_b128 v[208:211], v154 offset:38912
	ds_read_b128 v[216:219], v154 offset:39936
	global_load_lds_dwordx4 v[224:225], off
	v_lshl_add_u64 v[224:225], s[16:17], 0, v[134:135]
	s_mov_b32 m0, s41
	s_nop 0
	global_load_lds_dwordx4 v[224:225], off
	s_waitcnt vmcnt(8)
	s_waitcnt lgkmcnt(0)
	s_barrier
	s_waitcnt lgkmcnt(0)
	v_mfma_f32_16x16x32_bf16 v[126:129], v[144:147], v[184:187], v[126:129]
	v_mfma_f32_16x16x32_bf16 v[122:125], v[160:163], v[184:187], v[122:125]
	v_mfma_f32_16x16x32_bf16 v[110:113], v[144:147], v[192:195], v[110:113]
	v_mfma_f32_16x16x32_bf16 v[106:109], v[160:163], v[192:195], v[106:109]
	v_mfma_f32_16x16x32_bf16 v[94:97], v[144:147], v[200:203], v[94:97]
	v_mfma_f32_16x16x32_bf16 v[90:93], v[160:163], v[200:203], v[90:93]
	v_mfma_f32_16x16x32_bf16 v[78:81], v[144:147], v[208:211], v[78:81]
	v_mfma_f32_16x16x32_bf16 v[74:77], v[160:163], v[208:211], v[74:77]
	v_mfma_f32_16x16x32_bf16 v[126:129], v[156:159], v[188:191], v[126:129]
	v_mfma_f32_16x16x32_bf16 v[122:125], v[164:167], v[188:191], v[122:125]
	v_mfma_f32_16x16x32_bf16 v[110:113], v[156:159], v[196:199], v[110:113]
	v_mfma_f32_16x16x32_bf16 v[106:109], v[164:167], v[196:199], v[106:109]
	v_mfma_f32_16x16x32_bf16 v[94:97], v[156:159], v[204:207], v[94:97]
	v_mfma_f32_16x16x32_bf16 v[90:93], v[164:167], v[204:207], v[90:93]
	v_mfma_f32_16x16x32_bf16 v[78:81], v[156:159], v[216:219], v[78:81]
	v_mfma_f32_16x16x32_bf16 v[74:77], v[164:167], v[216:219], v[74:77]
	v_mfma_f32_16x16x32_bf16 v[118:121], v[168:171], v[184:187], v[118:121]
	v_mfma_f32_16x16x32_bf16 v[114:117], v[176:179], v[184:187], v[114:117]
	v_mfma_f32_16x16x32_bf16 v[102:105], v[168:171], v[192:195], v[102:105]
	v_mfma_f32_16x16x32_bf16 v[98:101], v[176:179], v[192:195], v[98:101]
	v_mfma_f32_16x16x32_bf16 v[86:89], v[168:171], v[200:203], v[86:89]
	v_mfma_f32_16x16x32_bf16 v[82:85], v[176:179], v[200:203], v[82:85]
	v_mfma_f32_16x16x32_bf16 v[70:73], v[168:171], v[208:211], v[70:73]
	v_mfma_f32_16x16x32_bf16 v[66:69], v[176:179], v[208:211], v[66:69]
	v_mfma_f32_16x16x32_bf16 v[118:121], v[172:175], v[188:191], v[118:121]
	v_mfma_f32_16x16x32_bf16 v[114:117], v[180:183], v[188:191], v[114:117]
	v_mfma_f32_16x16x32_bf16 v[102:105], v[172:175], v[196:199], v[102:105]
	v_mfma_f32_16x16x32_bf16 v[98:101], v[180:183], v[196:199], v[98:101]
	v_mfma_f32_16x16x32_bf16 v[86:89], v[172:175], v[204:207], v[86:89]
	v_mfma_f32_16x16x32_bf16 v[82:85], v[180:183], v[204:207], v[82:85]
	v_mfma_f32_16x16x32_bf16 v[70:73], v[172:175], v[216:219], v[70:73]
	v_mfma_f32_16x16x32_bf16 v[66:69], v[180:183], v[216:219], v[66:69]
	s_barrier
	s_add_i32 s16, s54, s28
	v_lshl_add_u64 v[148:149], v[148:149], 0, s[18:19]
	s_mov_b32 m0, s16
	ds_read_b128 v[184:187], v154 offset:49152
	ds_read_b128 v[188:191], v154 offset:50176
	ds_read_b128 v[192:195], v154 offset:51200
	ds_read_b128 v[196:199], v154 offset:52224
	ds_read_b128 v[200:203], v154 offset:53248
	ds_read_b128 v[204:207], v154 offset:54272
	ds_read_b128 v[208:211], v154 offset:55296
	ds_read_b128 v[216:219], v154 offset:56320
	global_load_lds_dwordx4 v[148:149], off
	s_add_i32 m0, s16, 0x2000
	s_add_u32 s16, s24, 0x2b0080
	v_lshl_add_u64 v[148:149], v[212:213], 0, s[18:19]
	s_addc_u32 s17, s25, 0
	s_add_i32 s24, s55, s28
	global_load_lds_dwordx4 v[148:149], off
	v_lshl_add_u64 v[148:149], s[16:17], 0, v[130:131]
	s_mov_b32 m0, s24
	s_nop 0
	global_load_lds_dwordx4 v[148:149], off
	v_lshl_add_u64 v[148:149], s[16:17], 0, v[132:133]
	s_add_i32 m0, s24, 0x2000
	s_nop 0
	global_load_lds_dwordx4 v[148:149], off
	v_lshl_add_u64 v[148:149], v[220:221], 0, s[18:19]
	s_mov_b32 m0, s44
	s_nop 0
	global_load_lds_dwordx4 v[148:149], off
	v_lshl_add_u64 v[148:149], v[222:223], 0, s[18:19]
	s_mov_b32 m0, s45
	s_nop 0
	global_load_lds_dwordx4 v[148:149], off
	s_waitcnt vmcnt(8)
	s_waitcnt lgkmcnt(0)
	s_barrier
	s_waitcnt lgkmcnt(0)
	v_mfma_f32_16x16x32_bf16 v[62:65], v[144:147], v[184:187], v[62:65]
	v_mfma_f32_16x16x32_bf16 v[58:61], v[160:163], v[184:187], v[58:61]
	v_mfma_f32_16x16x32_bf16 v[46:49], v[144:147], v[192:195], v[46:49]
	v_mfma_f32_16x16x32_bf16 v[42:45], v[160:163], v[192:195], v[42:45]
	v_mfma_f32_16x16x32_bf16 v[30:33], v[144:147], v[200:203], v[30:33]
	v_mfma_f32_16x16x32_bf16 v[26:29], v[160:163], v[200:203], v[26:29]
	v_mfma_f32_16x16x32_bf16 v[14:17], v[144:147], v[208:211], v[14:17]
	v_mfma_f32_16x16x32_bf16 v[10:13], v[160:163], v[208:211], v[10:13]
	v_mfma_f32_16x16x32_bf16 v[62:65], v[156:159], v[188:191], v[62:65]
	v_mfma_f32_16x16x32_bf16 v[58:61], v[164:167], v[188:191], v[58:61]
	v_mfma_f32_16x16x32_bf16 v[46:49], v[156:159], v[196:199], v[46:49]
	v_mfma_f32_16x16x32_bf16 v[42:45], v[164:167], v[196:199], v[42:45]
	v_mfma_f32_16x16x32_bf16 v[30:33], v[156:159], v[204:207], v[30:33]
	v_mfma_f32_16x16x32_bf16 v[26:29], v[164:167], v[204:207], v[26:29]
	v_mfma_f32_16x16x32_bf16 v[14:17], v[156:159], v[216:219], v[14:17]
	v_mfma_f32_16x16x32_bf16 v[10:13], v[164:167], v[216:219], v[10:13]
	v_mfma_f32_16x16x32_bf16 v[54:57], v[168:171], v[184:187], v[54:57]
	v_mfma_f32_16x16x32_bf16 v[50:53], v[176:179], v[184:187], v[50:53]
	v_mfma_f32_16x16x32_bf16 v[38:41], v[168:171], v[192:195], v[38:41]
	v_mfma_f32_16x16x32_bf16 v[34:37], v[176:179], v[192:195], v[34:37]
	v_mfma_f32_16x16x32_bf16 v[22:25], v[168:171], v[200:203], v[22:25]
	v_mfma_f32_16x16x32_bf16 v[18:21], v[176:179], v[200:203], v[18:21]
	v_mfma_f32_16x16x32_bf16 v[6:9], v[168:171], v[208:211], v[6:9]
	v_mfma_f32_16x16x32_bf16 v[2:5], v[176:179], v[208:211], v[2:5]
	v_mfma_f32_16x16x32_bf16 v[54:57], v[172:175], v[188:191], v[54:57]
	v_mfma_f32_16x16x32_bf16 v[50:53], v[180:183], v[188:191], v[50:53]
	v_mfma_f32_16x16x32_bf16 v[38:41], v[172:175], v[196:199], v[38:41]
	v_mfma_f32_16x16x32_bf16 v[34:37], v[180:183], v[196:199], v[34:37]
	v_mfma_f32_16x16x32_bf16 v[22:25], v[172:175], v[204:207], v[22:25]
	v_mfma_f32_16x16x32_bf16 v[18:21], v[180:183], v[204:207], v[18:21]
	v_mfma_f32_16x16x32_bf16 v[6:9], v[172:175], v[216:219], v[6:9]
	v_mfma_f32_16x16x32_bf16 v[2:5], v[180:183], v[216:219], v[2:5]
	s_add_i32 s53, s53, 2
	s_add_u32 s51, s51, 0x100
	s_addc_u32 s52, s52, 0
	s_cmpk_gt_u32 s53, 0xa9
	s_mov_b64 s[16:17], s[22:23]
	s_barrier
	s_cbranch_scc0 .LBB0_1405
	s_and_b64 vcc, exec, s[6:7]
	s_cbranch_vccz .LBB0_1408
	s_barrier
